# GEMM unit start: first SP1 load-issue peeled ahead of the 128 accumulator zero moves (zeroing overlaps LDS latency)
# baseline (speedup 1.0000x reference)
.LBB0_204:
	s_ashr_i32 s27, s26, 31
	s_lshl_b64 s[16:17], s[26:27], 20
	s_add_u32 s38, s0, s16
	s_addc_u32 s39, s1, s17
	s_and_b64 s[16:17], s[36:37], exec
	s_cselect_b32 s27, s39, s43
	s_cselect_b32 s73, s38, s42
	s_ashr_i32 s23, s22, 31
	s_lshl_b64 s[16:17], s[22:23], 20
	v_readlane_b32 s23, v255, 4
	s_add_u32 s40, s23, s16
	v_readlane_b32 s16, v255, 5
	s_addc_u32 s41, s16, s17
	s_and_b64 s[16:17], s[36:37], exec
	s_cselect_b32 s23, s41, s29
	s_cselect_b32 s74, s40, s28
	s_add_u32 s42, s42, 0x80080
	s_addc_u32 s43, s43, 0
	s_add_u32 s77, s28, 0x100
	s_addc_u32 s78, s29, 0
	s_mov_b32 s88, -2
	s_waitcnt lgkmcnt(0)
	s_waitcnt vmcnt(0)
	s_add_u32 s16, s42, 0xfff80080
	s_addc_u32 s17, s43, -1
	s_add_i32 s89, 0, 0x10000
	s_cmp_eq_u32 s88, 28
	s_cselect_b32 s45, s27, s17
	s_cselect_b32 s44, s73, s16
	s_cselect_b32 s29, s23, s78
	s_cselect_b32 s28, s74, s77
	s_add_i32 s91, 0, 0x14000
	v_add_u32_e32 v144, s89, v227
	v_add_u32_e32 v170, s91, v227
	ds_read_b128 v[132:135], v144
	ds_read_b128 v[136:139], v144 offset:1024
	ds_read_b128 v[140:143], v144 offset:2048
	ds_read_b128 v[144:147], v144 offset:3072
	ds_read_b128 v[148:151], v170
	ds_read_b128 v[152:155], v170 offset:1024
	ds_read_b128 v[166:169], v170 offset:2048
	ds_read_b128 v[170:173], v170 offset:3072
	v_lshl_add_u64 v[216:217], s[42:43], 0, v[162:163]
	s_add_i32 m0, s31, 0xc000
	ds_read_b128 v[184:187], v229
	ds_read_b128 v[188:191], v229 offset:1024
	ds_read_b128 v[192:195], v229 offset:2048
	ds_read_b128 v[196:199], v229 offset:3072
	ds_read_b128 v[200:203], v229 offset:4096
	ds_read_b128 v[204:207], v229 offset:5120
	ds_read_b128 v[208:211], v229 offset:6144
	ds_read_b128 v[212:215], v229 offset:7168
	global_load_lds_dwordx4 v[216:217], off
	v_lshl_add_u64 v[216:217], s[42:43], 0, v[164:165]
	s_add_i32 m0, s31, 0xe000
	s_nop 0
	global_load_lds_dwordx4 v[216:217], off
	v_mov_b32_e32 v4, 0
	v_mov_b32_e32 v5, v4
	v_mov_b32_e32 v6, v4
	v_mov_b32_e32 v7, v4
	v_mov_b32_e32 v8, v4
	v_mov_b32_e32 v9, v4
	v_mov_b32_e32 v10, v4
	v_mov_b32_e32 v11, v4
	v_mov_b32_e32 v20, v4
	v_mov_b32_e32 v21, v4
	v_mov_b32_e32 v22, v4
	v_mov_b32_e32 v23, v4
	v_mov_b32_e32 v24, v4
	v_mov_b32_e32 v25, v4
	v_mov_b32_e32 v26, v4
	v_mov_b32_e32 v27, v4
	v_mov_b32_e32 v36, v4
	v_mov_b32_e32 v37, v4
	v_mov_b32_e32 v38, v4
	v_mov_b32_e32 v39, v4
	v_mov_b32_e32 v40, v4
	v_mov_b32_e32 v41, v4
	v_mov_b32_e32 v42, v4
	v_mov_b32_e32 v43, v4
	v_mov_b32_e32 v52, v4
	v_mov_b32_e32 v53, v4
	v_mov_b32_e32 v54, v4
	v_mov_b32_e32 v55, v4
	v_mov_b32_e32 v56, v4
	v_mov_b32_e32 v57, v4
	v_mov_b32_e32 v58, v4
	v_mov_b32_e32 v59, v4
	v_mov_b32_e32 v12, v4
	v_mov_b32_e32 v13, v4
	v_mov_b32_e32 v14, v4
	v_mov_b32_e32 v15, v4
	v_mov_b32_e32 v16, v4
	v_mov_b32_e32 v17, v4
	v_mov_b32_e32 v18, v4
	v_mov_b32_e32 v19, v4
	v_mov_b32_e32 v28, v4
	v_mov_b32_e32 v29, v4
	v_mov_b32_e32 v30, v4
	v_mov_b32_e32 v31, v4
	v_mov_b32_e32 v32, v4
	v_mov_b32_e32 v33, v4
	v_mov_b32_e32 v34, v4
	v_mov_b32_e32 v35, v4
	v_mov_b32_e32 v44, v4
	v_mov_b32_e32 v45, v4
	v_mov_b32_e32 v46, v4
	v_mov_b32_e32 v47, v4
	v_mov_b32_e32 v48, v4
	v_mov_b32_e32 v49, v4
	v_mov_b32_e32 v50, v4
	v_mov_b32_e32 v51, v4
	v_mov_b32_e32 v60, v4
	v_mov_b32_e32 v61, v4
	v_mov_b32_e32 v62, v4
	v_mov_b32_e32 v63, v4
	v_mov_b32_e32 v64, v4
	v_mov_b32_e32 v65, v4
	v_mov_b32_e32 v66, v4
	v_mov_b32_e32 v67, v4
	v_mov_b32_e32 v68, v4
	v_mov_b32_e32 v69, v4
	v_mov_b32_e32 v70, v4
	v_mov_b32_e32 v71, v4
	v_mov_b32_e32 v72, v4
	v_mov_b32_e32 v73, v4
	v_mov_b32_e32 v74, v4
	v_mov_b32_e32 v75, v4
	v_mov_b32_e32 v84, v4
	v_mov_b32_e32 v85, v4
	v_mov_b32_e32 v86, v4
	v_mov_b32_e32 v87, v4
	v_mov_b32_e32 v88, v4
	v_mov_b32_e32 v89, v4
	v_mov_b32_e32 v90, v4
	v_mov_b32_e32 v91, v4
	v_mov_b32_e32 v100, v4
	v_mov_b32_e32 v101, v4
	v_mov_b32_e32 v102, v4
	v_mov_b32_e32 v103, v4
	v_mov_b32_e32 v104, v4
	v_mov_b32_e32 v105, v4
	v_mov_b32_e32 v106, v4
	v_mov_b32_e32 v107, v4
	v_mov_b32_e32 v116, v4
	v_mov_b32_e32 v117, v4
	v_mov_b32_e32 v118, v4
	v_mov_b32_e32 v119, v4
	v_mov_b32_e32 v120, v4
	v_mov_b32_e32 v121, v4
	v_mov_b32_e32 v122, v4
	v_mov_b32_e32 v123, v4
	v_mov_b32_e32 v76, v4
	v_mov_b32_e32 v77, v4
	v_mov_b32_e32 v78, v4
	v_mov_b32_e32 v79, v4
	v_mov_b32_e32 v80, v4
	v_mov_b32_e32 v81, v4
	v_mov_b32_e32 v82, v4
	v_mov_b32_e32 v83, v4
	v_mov_b32_e32 v92, v4
	v_mov_b32_e32 v93, v4
	v_mov_b32_e32 v94, v4
	v_mov_b32_e32 v95, v4
	v_mov_b32_e32 v96, v4
	v_mov_b32_e32 v97, v4
	v_mov_b32_e32 v98, v4
	v_mov_b32_e32 v99, v4
	v_mov_b32_e32 v108, v4
	v_mov_b32_e32 v109, v4
	v_mov_b32_e32 v110, v4
	v_mov_b32_e32 v111, v4
	v_mov_b32_e32 v112, v4
	v_mov_b32_e32 v113, v4
	v_mov_b32_e32 v114, v4
	v_mov_b32_e32 v115, v4
	v_mov_b32_e32 v124, v4
	v_mov_b32_e32 v125, v4
	v_mov_b32_e32 v126, v4
	v_mov_b32_e32 v127, v4
	v_mov_b32_e32 v128, v4
	v_mov_b32_e32 v129, v4
	v_mov_b32_e32 v130, v4
	v_mov_b32_e32 v131, v4
	s_branch .Lmid_205

.Lmid_205:
	s_waitcnt vmcnt(8)
	s_waitcnt lgkmcnt(0)
	s_setprio 1
	s_barrier
	v_mfma_f32_16x16x32_bf16 v[128:131], v[132:135], v[184:187], v[128:131]
	v_mfma_f32_16x16x32_bf16 v[124:127], v[140:143], v[184:187], v[124:127]
	v_mfma_f32_16x16x32_bf16 v[112:115], v[132:135], v[192:195], v[112:115]
	v_mfma_f32_16x16x32_bf16 v[108:111], v[140:143], v[192:195], v[108:111]
	v_mfma_f32_16x16x32_bf16 v[96:99], v[132:135], v[200:203], v[96:99]
	v_mfma_f32_16x16x32_bf16 v[92:95], v[140:143], v[200:203], v[92:95]
	v_mfma_f32_16x16x32_bf16 v[80:83], v[132:135], v[208:211], v[80:83]
	v_mfma_f32_16x16x32_bf16 v[76:79], v[140:143], v[208:211], v[76:79]
	v_mfma_f32_16x16x32_bf16 v[128:131], v[136:139], v[188:191], v[128:131]
	v_mfma_f32_16x16x32_bf16 v[124:127], v[144:147], v[188:191], v[124:127]
	v_mfma_f32_16x16x32_bf16 v[112:115], v[136:139], v[196:199], v[112:115]
	v_mfma_f32_16x16x32_bf16 v[108:111], v[144:147], v[196:199], v[108:111]
	v_mfma_f32_16x16x32_bf16 v[96:99], v[136:139], v[204:207], v[96:99]
	v_mfma_f32_16x16x32_bf16 v[92:95], v[144:147], v[204:207], v[92:95]
	v_mfma_f32_16x16x32_bf16 v[80:83], v[136:139], v[212:215], v[80:83]
	v_mfma_f32_16x16x32_bf16 v[76:79], v[144:147], v[212:215], v[76:79]
	v_mfma_f32_16x16x32_bf16 v[120:123], v[148:151], v[184:187], v[120:123]
	v_mfma_f32_16x16x32_bf16 v[116:119], v[166:169], v[184:187], v[116:119]
	v_mfma_f32_16x16x32_bf16 v[104:107], v[148:151], v[192:195], v[104:107]
	v_mfma_f32_16x16x32_bf16 v[100:103], v[166:169], v[192:195], v[100:103]
	v_mfma_f32_16x16x32_bf16 v[88:91], v[148:151], v[200:203], v[88:91]
	v_mfma_f32_16x16x32_bf16 v[84:87], v[166:169], v[200:203], v[84:87]
	v_mfma_f32_16x16x32_bf16 v[72:75], v[148:151], v[208:211], v[72:75]
	v_mfma_f32_16x16x32_bf16 v[68:71], v[166:169], v[208:211], v[68:71]
	v_mfma_f32_16x16x32_bf16 v[120:123], v[152:155], v[188:191], v[120:123]
	v_mfma_f32_16x16x32_bf16 v[116:119], v[170:173], v[188:191], v[116:119]
	v_mfma_f32_16x16x32_bf16 v[104:107], v[152:155], v[196:199], v[104:107]
	v_mfma_f32_16x16x32_bf16 v[100:103], v[170:173], v[196:199], v[100:103]
	v_mfma_f32_16x16x32_bf16 v[88:91], v[152:155], v[204:207], v[88:91]
	v_mfma_f32_16x16x32_bf16 v[84:87], v[170:173], v[204:207], v[84:87]
	v_mfma_f32_16x16x32_bf16 v[72:75], v[152:155], v[212:215], v[72:75]
	v_mfma_f32_16x16x32_bf16 v[68:71], v[170:173], v[212:215], v[68:71]
	s_barrier
	s_setprio 0
	s_add_i32 s16, s89, s3
	v_lshl_add_u64 v[216:217], s[28:29], 0, v[2:3]
	s_mov_b32 m0, s16
	ds_read_b128 v[184:187], v229 offset:16384
	ds_read_b128 v[188:191], v229 offset:17408
	ds_read_b128 v[192:195], v229 offset:18432
	ds_read_b128 v[196:199], v229 offset:19456
	ds_read_b128 v[200:203], v229 offset:20480
	ds_read_b128 v[204:207], v229 offset:21504
	ds_read_b128 v[208:211], v229 offset:22528
	ds_read_b128 v[212:215], v229 offset:23552
	global_load_lds_dwordx4 v[216:217], off
	s_add_i32 m0, s16, 0x2000
	s_add_u32 s16, s28, 0x80000
	v_lshl_add_u64 v[218:219], s[28:29], 0, v[156:157]
	s_addc_u32 s17, s29, 0
	s_add_i32 s89, s91, s3
	global_load_lds_dwordx4 v[218:219], off
	v_lshl_add_u64 v[220:221], s[16:17], 0, v[2:3]
	s_mov_b32 m0, s89
	v_lshl_add_u64 v[222:223], s[44:45], 0, v[158:159]
	global_load_lds_dwordx4 v[220:221], off
	v_lshl_add_u64 v[220:221], s[16:17], 0, v[156:157]
	s_add_i32 m0, s89, 0x2000
	s_nop 0
	global_load_lds_dwordx4 v[220:221], off
	v_lshl_add_u64 v[220:221], s[44:45], 0, v[160:161]
	s_mov_b32 m0, s31
	s_nop 0
	global_load_lds_dwordx4 v[220:221], off
	s_mov_b32 m0, s33
	s_nop 0
	global_load_lds_dwordx4 v[222:223], off
	s_waitcnt vmcnt(8)
	s_waitcnt lgkmcnt(0)
	s_setprio 1
	s_barrier
	v_mfma_f32_16x16x32_bf16 v[64:67], v[132:135], v[184:187], v[64:67]
	v_mfma_f32_16x16x32_bf16 v[60:63], v[140:143], v[184:187], v[60:63]
	v_mfma_f32_16x16x32_bf16 v[48:51], v[132:135], v[192:195], v[48:51]
	v_mfma_f32_16x16x32_bf16 v[44:47], v[140:143], v[192:195], v[44:47]
	v_mfma_f32_16x16x32_bf16 v[32:35], v[132:135], v[200:203], v[32:35]
	v_mfma_f32_16x16x32_bf16 v[28:31], v[140:143], v[200:203], v[28:31]
	v_mfma_f32_16x16x32_bf16 v[16:19], v[132:135], v[208:211], v[16:19]
	v_mfma_f32_16x16x32_bf16 v[12:15], v[140:143], v[208:211], v[12:15]
	v_mfma_f32_16x16x32_bf16 v[64:67], v[136:139], v[188:191], v[64:67]
	v_mfma_f32_16x16x32_bf16 v[60:63], v[144:147], v[188:191], v[60:63]
	v_mfma_f32_16x16x32_bf16 v[48:51], v[136:139], v[196:199], v[48:51]
	v_mfma_f32_16x16x32_bf16 v[44:47], v[144:147], v[196:199], v[44:47]
	v_mfma_f32_16x16x32_bf16 v[32:35], v[136:139], v[204:207], v[32:35]
	v_mfma_f32_16x16x32_bf16 v[28:31], v[144:147], v[204:207], v[28:31]
	v_mfma_f32_16x16x32_bf16 v[16:19], v[136:139], v[212:215], v[16:19]
	v_mfma_f32_16x16x32_bf16 v[12:15], v[144:147], v[212:215], v[12:15]
	v_mfma_f32_16x16x32_bf16 v[56:59], v[148:151], v[184:187], v[56:59]
	v_mfma_f32_16x16x32_bf16 v[52:55], v[166:169], v[184:187], v[52:55]
	v_mfma_f32_16x16x32_bf16 v[40:43], v[148:151], v[192:195], v[40:43]
	v_mfma_f32_16x16x32_bf16 v[36:39], v[166:169], v[192:195], v[36:39]
	v_mfma_f32_16x16x32_bf16 v[24:27], v[148:151], v[200:203], v[24:27]
	v_mfma_f32_16x16x32_bf16 v[20:23], v[166:169], v[200:203], v[20:23]
	v_mfma_f32_16x16x32_bf16 v[8:11], v[148:151], v[208:211], v[8:11]
	v_mfma_f32_16x16x32_bf16 v[4:7], v[166:169], v[208:211], v[4:7]
	v_mfma_f32_16x16x32_bf16 v[56:59], v[152:155], v[188:191], v[56:59]
	v_mfma_f32_16x16x32_bf16 v[52:55], v[170:173], v[188:191], v[52:55]
	v_mfma_f32_16x16x32_bf16 v[40:43], v[152:155], v[196:199], v[40:43]
	v_mfma_f32_16x16x32_bf16 v[36:39], v[170:173], v[196:199], v[36:39]
	v_mfma_f32_16x16x32_bf16 v[24:27], v[152:155], v[204:207], v[24:27]
	v_mfma_f32_16x16x32_bf16 v[20:23], v[170:173], v[204:207], v[20:23]
	v_mfma_f32_16x16x32_bf16 v[8:11], v[152:155], v[212:215], v[8:11]
	v_mfma_f32_16x16x32_bf16 v[4:7], v[170:173], v[212:215], v[4:7]
	s_barrier
	s_setprio 0
	s_add_i32 s89, 0, 0x18000
	s_add_i32 s91, 0, 0x1c000
	v_add_u32_e32 v144, s89, v227
	v_add_u32_e32 v170, s91, v227
	ds_read_b128 v[132:135], v144
	ds_read_b128 v[136:139], v144 offset:1024
	ds_read_b128 v[140:143], v144 offset:2048
	ds_read_b128 v[144:147], v144 offset:3072
	ds_read_b128 v[148:151], v170
	ds_read_b128 v[152:155], v170 offset:1024
	ds_read_b128 v[166:169], v170 offset:2048
	ds_read_b128 v[170:173], v170 offset:3072
	s_add_u32 s16, s44, 0x80000
	s_addc_u32 s17, s45, 0
	s_mov_b32 m0, s46
	v_lshl_add_u64 v[224:225], s[16:17], 0, v[160:161]
	ds_read_b128 v[184:187], v229 offset:32768
	ds_read_b128 v[188:191], v229 offset:33792
	ds_read_b128 v[192:195], v229 offset:34816
	ds_read_b128 v[196:199], v229 offset:35840
	ds_read_b128 v[200:203], v229 offset:36864
	ds_read_b128 v[204:207], v229 offset:37888
	ds_read_b128 v[208:211], v229 offset:38912
	ds_read_b128 v[212:215], v229 offset:39936
	global_load_lds_dwordx4 v[224:225], off
	v_lshl_add_u64 v[224:225], s[16:17], 0, v[158:159]
	s_mov_b32 m0, s47
	s_nop 0
	global_load_lds_dwordx4 v[224:225], off
	s_waitcnt vmcnt(8)
	s_waitcnt lgkmcnt(0)
	s_setprio 1
	s_barrier
	v_mfma_f32_16x16x32_bf16 v[128:131], v[132:135], v[184:187], v[128:131]
	v_mfma_f32_16x16x32_bf16 v[124:127], v[140:143], v[184:187], v[124:127]
	v_mfma_f32_16x16x32_bf16 v[112:115], v[132:135], v[192:195], v[112:115]
	v_mfma_f32_16x16x32_bf16 v[108:111], v[140:143], v[192:195], v[108:111]
	v_mfma_f32_16x16x32_bf16 v[96:99], v[132:135], v[200:203], v[96:99]
	v_mfma_f32_16x16x32_bf16 v[92:95], v[140:143], v[200:203], v[92:95]
	v_mfma_f32_16x16x32_bf16 v[80:83], v[132:135], v[208:211], v[80:83]
	v_mfma_f32_16x16x32_bf16 v[76:79], v[140:143], v[208:211], v[76:79]
	v_mfma_f32_16x16x32_bf16 v[128:131], v[136:139], v[188:191], v[128:131]
	v_mfma_f32_16x16x32_bf16 v[124:127], v[144:147], v[188:191], v[124:127]
	v_mfma_f32_16x16x32_bf16 v[112:115], v[136:139], v[196:199], v[112:115]
	v_mfma_f32_16x16x32_bf16 v[108:111], v[144:147], v[196:199], v[108:111]
	v_mfma_f32_16x16x32_bf16 v[96:99], v[136:139], v[204:207], v[96:99]
	v_mfma_f32_16x16x32_bf16 v[92:95], v[144:147], v[204:207], v[92:95]
	v_mfma_f32_16x16x32_bf16 v[80:83], v[136:139], v[212:215], v[80:83]
	v_mfma_f32_16x16x32_bf16 v[76:79], v[144:147], v[212:215], v[76:79]
	v_mfma_f32_16x16x32_bf16 v[120:123], v[148:151], v[184:187], v[120:123]
	v_mfma_f32_16x16x32_bf16 v[116:119], v[166:169], v[184:187], v[116:119]
	v_mfma_f32_16x16x32_bf16 v[104:107], v[148:151], v[192:195], v[104:107]
	v_mfma_f32_16x16x32_bf16 v[100:103], v[166:169], v[192:195], v[100:103]
	v_mfma_f32_16x16x32_bf16 v[88:91], v[148:151], v[200:203], v[88:91]
	v_mfma_f32_16x16x32_bf16 v[84:87], v[166:169], v[200:203], v[84:87]
	v_mfma_f32_16x16x32_bf16 v[72:75], v[148:151], v[208:211], v[72:75]
	v_mfma_f32_16x16x32_bf16 v[68:71], v[166:169], v[208:211], v[68:71]
	v_mfma_f32_16x16x32_bf16 v[120:123], v[152:155], v[188:191], v[120:123]
	v_mfma_f32_16x16x32_bf16 v[116:119], v[170:173], v[188:191], v[116:119]
	v_mfma_f32_16x16x32_bf16 v[104:107], v[152:155], v[196:199], v[104:107]
	v_mfma_f32_16x16x32_bf16 v[100:103], v[170:173], v[196:199], v[100:103]
	v_mfma_f32_16x16x32_bf16 v[88:91], v[152:155], v[204:207], v[88:91]
	v_mfma_f32_16x16x32_bf16 v[84:87], v[170:173], v[204:207], v[84:87]
	v_mfma_f32_16x16x32_bf16 v[72:75], v[152:155], v[212:215], v[72:75]
	v_mfma_f32_16x16x32_bf16 v[68:71], v[170:173], v[212:215], v[68:71]
	s_barrier
	s_setprio 0
	s_add_i32 s16, s89, s3
	v_lshl_add_u64 v[216:217], v[216:217], 0, s[24:25]
	s_mov_b32 m0, s16
	ds_read_b128 v[184:187], v229 offset:49152
	ds_read_b128 v[188:191], v229 offset:50176
	ds_read_b128 v[192:195], v229 offset:51200
	ds_read_b128 v[196:199], v229 offset:52224
	ds_read_b128 v[200:203], v229 offset:53248
	ds_read_b128 v[204:207], v229 offset:54272
	ds_read_b128 v[208:211], v229 offset:55296
	ds_read_b128 v[212:215], v229 offset:56320
	global_load_lds_dwordx4 v[216:217], off
	s_add_i32 m0, s16, 0x2000
	s_add_u32 s16, s28, 0x80080
	v_lshl_add_u64 v[216:217], v[218:219], 0, s[24:25]
	s_addc_u32 s17, s29, 0
	s_add_i32 s28, s91, s3
	global_load_lds_dwordx4 v[216:217], off
	v_lshl_add_u64 v[216:217], s[16:17], 0, v[2:3]
	s_mov_b32 m0, s28
	s_nop 0
	global_load_lds_dwordx4 v[216:217], off
	v_lshl_add_u64 v[216:217], s[16:17], 0, v[156:157]
	s_add_i32 m0, s28, 0x2000
	s_nop 0
	global_load_lds_dwordx4 v[216:217], off
	v_lshl_add_u64 v[216:217], v[220:221], 0, s[24:25]
	s_mov_b32 m0, s48
	s_nop 0
	global_load_lds_dwordx4 v[216:217], off
	v_lshl_add_u64 v[216:217], v[222:223], 0, s[24:25]
	s_mov_b32 m0, s49
	s_nop 0
	global_load_lds_dwordx4 v[216:217], off
	s_waitcnt vmcnt(8)
	s_waitcnt lgkmcnt(0)
	s_setprio 1
	s_barrier
	v_mfma_f32_16x16x32_bf16 v[64:67], v[132:135], v[184:187], v[64:67]
	v_mfma_f32_16x16x32_bf16 v[60:63], v[140:143], v[184:187], v[60:63]
	v_mfma_f32_16x16x32_bf16 v[48:51], v[132:135], v[192:195], v[48:51]
	v_mfma_f32_16x16x32_bf16 v[44:47], v[140:143], v[192:195], v[44:47]
	v_mfma_f32_16x16x32_bf16 v[32:35], v[132:135], v[200:203], v[32:35]
	v_mfma_f32_16x16x32_bf16 v[28:31], v[140:143], v[200:203], v[28:31]
	v_mfma_f32_16x16x32_bf16 v[16:19], v[132:135], v[208:211], v[16:19]
	v_mfma_f32_16x16x32_bf16 v[12:15], v[140:143], v[208:211], v[12:15]
	v_mfma_f32_16x16x32_bf16 v[64:67], v[136:139], v[188:191], v[64:67]
	v_mfma_f32_16x16x32_bf16 v[60:63], v[144:147], v[188:191], v[60:63]
	v_mfma_f32_16x16x32_bf16 v[48:51], v[136:139], v[196:199], v[48:51]
	v_mfma_f32_16x16x32_bf16 v[44:47], v[144:147], v[196:199], v[44:47]
	v_mfma_f32_16x16x32_bf16 v[32:35], v[136:139], v[204:207], v[32:35]
	v_mfma_f32_16x16x32_bf16 v[28:31], v[144:147], v[204:207], v[28:31]
	v_mfma_f32_16x16x32_bf16 v[16:19], v[136:139], v[212:215], v[16:19]
	v_mfma_f32_16x16x32_bf16 v[12:15], v[144:147], v[212:215], v[12:15]
	v_mfma_f32_16x16x32_bf16 v[56:59], v[148:151], v[184:187], v[56:59]
	v_mfma_f32_16x16x32_bf16 v[52:55], v[166:169], v[184:187], v[52:55]
	v_mfma_f32_16x16x32_bf16 v[40:43], v[148:151], v[192:195], v[40:43]
	v_mfma_f32_16x16x32_bf16 v[36:39], v[166:169], v[192:195], v[36:39]
	v_mfma_f32_16x16x32_bf16 v[24:27], v[148:151], v[200:203], v[24:27]
	v_mfma_f32_16x16x32_bf16 v[20:23], v[166:169], v[200:203], v[20:23]
	v_mfma_f32_16x16x32_bf16 v[8:11], v[148:151], v[208:211], v[8:11]
	v_mfma_f32_16x16x32_bf16 v[4:7], v[166:169], v[208:211], v[4:7]
	v_mfma_f32_16x16x32_bf16 v[56:59], v[152:155], v[188:191], v[56:59]
	v_mfma_f32_16x16x32_bf16 v[52:55], v[170:173], v[188:191], v[52:55]
	v_mfma_f32_16x16x32_bf16 v[40:43], v[152:155], v[196:199], v[40:43]
	v_mfma_f32_16x16x32_bf16 v[36:39], v[170:173], v[196:199], v[36:39]
	v_mfma_f32_16x16x32_bf16 v[24:27], v[152:155], v[204:207], v[24:27]
	v_mfma_f32_16x16x32_bf16 v[20:23], v[170:173], v[204:207], v[20:23]
	v_mfma_f32_16x16x32_bf16 v[8:11], v[152:155], v[212:215], v[8:11]
	v_mfma_f32_16x16x32_bf16 v[4:7], v[170:173], v[212:215], v[4:7]
	s_barrier
	s_setprio 0
	s_add_i32 s88, s88, 2
	s_add_u32 s42, s42, 0x100
	s_addc_u32 s43, s43, 0
	s_add_u32 s77, s77, 0x100
	s_addc_u32 s78, s78, 0
	s_cmp_gt_u32 s88, 29
	s_cbranch_scc0 .LBB0_205
	v_mov_b32_e32 v176, 0xc2000000

.LBB0_365:
	s_add_u32 s31, s28, 0x100
	s_addc_u32 s33, s29, 0
	s_mov_b32 s22, -2
	s_waitcnt lgkmcnt(0)
	s_waitcnt vmcnt(0)
	s_add_u32 s48, s50, 0x100
	s_addc_u32 s49, s51, 0
	s_add_i32 s16, 0, 0x10000
	s_cmpk_eq_i32 s22, 0x54
	s_cselect_b32 vcc_hi, s19, s49
	s_cselect_b32 vcc_lo, s18, s48
	s_cselect_b32 s29, s27, s33
	s_cselect_b32 s28, s26, s31
	s_add_i32 s23, 0, 0x14000
	v_add_u32_e32 v144, s16, v244
	v_add_u32_e32 v160, s23, v244
	ds_read_b128 v[132:135], v144
	ds_read_b128 v[136:139], v144 offset:1024
	ds_read_b128 v[140:143], v144 offset:2048
	ds_read_b128 v[144:147], v144 offset:3072
	ds_read_b128 v[148:151], v160
	ds_read_b128 v[152:155], v160 offset:1024
	ds_read_b128 v[156:159], v160 offset:2048
	ds_read_b128 v[160:163], v160 offset:3072
	v_lshl_add_u64 v[174:175], s[50:51], 0, v[184:185]
	s_add_i32 m0, s74, 0xc000
	ds_read_b128 v[164:167], v246
	ds_read_b128 v[188:191], v246 offset:1024
	ds_read_b128 v[192:195], v246 offset:2048
	ds_read_b128 v[196:199], v246 offset:3072
	ds_read_b128 v[200:203], v246 offset:4096
	ds_read_b128 v[204:207], v246 offset:5120
	ds_read_b128 v[208:211], v246 offset:6144
	ds_read_b128 v[212:215], v246 offset:7168
	global_load_lds_dwordx4 v[174:175], off
	v_lshl_add_u64 v[174:175], s[50:51], 0, v[186:187]
	s_add_i32 m0, s74, 0xe000
	s_nop 0
	global_load_lds_dwordx4 v[174:175], off
	v_mov_b32_e32 v4, 0
	v_mov_b32_e32 v5, v4
	v_mov_b32_e32 v6, v4
	v_mov_b32_e32 v7, v4
	v_mov_b32_e32 v8, v4
	v_mov_b32_e32 v9, v4
	v_mov_b32_e32 v10, v4
	v_mov_b32_e32 v11, v4
	v_mov_b32_e32 v20, v4
	v_mov_b32_e32 v21, v4
	v_mov_b32_e32 v22, v4
	v_mov_b32_e32 v23, v4
	v_mov_b32_e32 v24, v4
	v_mov_b32_e32 v25, v4
	v_mov_b32_e32 v26, v4
	v_mov_b32_e32 v27, v4
	v_mov_b32_e32 v36, v4
	v_mov_b32_e32 v37, v4
	v_mov_b32_e32 v38, v4
	v_mov_b32_e32 v39, v4
	v_mov_b32_e32 v40, v4
	v_mov_b32_e32 v41, v4
	v_mov_b32_e32 v42, v4
	v_mov_b32_e32 v43, v4
	v_mov_b32_e32 v52, v4
	v_mov_b32_e32 v53, v4
	v_mov_b32_e32 v54, v4
	v_mov_b32_e32 v55, v4
	v_mov_b32_e32 v56, v4
	v_mov_b32_e32 v57, v4
	v_mov_b32_e32 v58, v4
	v_mov_b32_e32 v59, v4
	v_mov_b32_e32 v12, v4
	v_mov_b32_e32 v13, v4
	v_mov_b32_e32 v14, v4
	v_mov_b32_e32 v15, v4
	v_mov_b32_e32 v16, v4
	v_mov_b32_e32 v17, v4
	v_mov_b32_e32 v18, v4
	v_mov_b32_e32 v19, v4
	v_mov_b32_e32 v28, v4
	v_mov_b32_e32 v29, v4
	v_mov_b32_e32 v30, v4
	v_mov_b32_e32 v31, v4
	v_mov_b32_e32 v32, v4
	v_mov_b32_e32 v33, v4
	v_mov_b32_e32 v34, v4
	v_mov_b32_e32 v35, v4
	v_mov_b32_e32 v44, v4
	v_mov_b32_e32 v45, v4
	v_mov_b32_e32 v46, v4
	v_mov_b32_e32 v47, v4
	v_mov_b32_e32 v48, v4
	v_mov_b32_e32 v49, v4
	v_mov_b32_e32 v50, v4
	v_mov_b32_e32 v51, v4
	v_mov_b32_e32 v60, v4
	v_mov_b32_e32 v61, v4
	v_mov_b32_e32 v62, v4
	v_mov_b32_e32 v63, v4
	v_mov_b32_e32 v64, v4
	v_mov_b32_e32 v65, v4
	v_mov_b32_e32 v66, v4
	v_mov_b32_e32 v67, v4
	v_mov_b32_e32 v68, v4
	v_mov_b32_e32 v69, v4
	v_mov_b32_e32 v70, v4
	v_mov_b32_e32 v71, v4
	v_mov_b32_e32 v72, v4
	v_mov_b32_e32 v73, v4
	v_mov_b32_e32 v74, v4
	v_mov_b32_e32 v75, v4
	v_mov_b32_e32 v84, v4
	v_mov_b32_e32 v85, v4
	v_mov_b32_e32 v86, v4
	v_mov_b32_e32 v87, v4
	v_mov_b32_e32 v88, v4
	v_mov_b32_e32 v89, v4
	v_mov_b32_e32 v90, v4
	v_mov_b32_e32 v91, v4
	v_mov_b32_e32 v100, v4
	v_mov_b32_e32 v101, v4
	v_mov_b32_e32 v102, v4
	v_mov_b32_e32 v103, v4
	v_mov_b32_e32 v104, v4
	v_mov_b32_e32 v105, v4
	v_mov_b32_e32 v106, v4
	v_mov_b32_e32 v107, v4
	v_mov_b32_e32 v116, v4
	v_mov_b32_e32 v117, v4
	v_mov_b32_e32 v118, v4
	v_mov_b32_e32 v119, v4
	v_mov_b32_e32 v120, v4
	v_mov_b32_e32 v121, v4
	v_mov_b32_e32 v122, v4
	v_mov_b32_e32 v123, v4
	v_mov_b32_e32 v76, v4
	v_mov_b32_e32 v77, v4
	v_mov_b32_e32 v78, v4
	v_mov_b32_e32 v79, v4
	v_mov_b32_e32 v80, v4
	v_mov_b32_e32 v81, v4
	v_mov_b32_e32 v82, v4
	v_mov_b32_e32 v83, v4
	v_mov_b32_e32 v92, v4
	v_mov_b32_e32 v93, v4
	v_mov_b32_e32 v94, v4
	v_mov_b32_e32 v95, v4
	v_mov_b32_e32 v96, v4
	v_mov_b32_e32 v97, v4
	v_mov_b32_e32 v98, v4
	v_mov_b32_e32 v99, v4
	v_mov_b32_e32 v108, v4
	v_mov_b32_e32 v109, v4
	v_mov_b32_e32 v110, v4
	v_mov_b32_e32 v111, v4
	v_mov_b32_e32 v112, v4
	v_mov_b32_e32 v113, v4
	v_mov_b32_e32 v114, v4
	v_mov_b32_e32 v115, v4
	v_mov_b32_e32 v124, v4
	v_mov_b32_e32 v125, v4
	v_mov_b32_e32 v126, v4
	v_mov_b32_e32 v127, v4
	v_mov_b32_e32 v128, v4
	v_mov_b32_e32 v129, v4
	v_mov_b32_e32 v130, v4
	v_mov_b32_e32 v131, v4
	s_branch .Lmid_366

.Lmid_366:
	s_waitcnt vmcnt(8)
	s_waitcnt lgkmcnt(0)
	s_setprio 1
	s_barrier
	v_mfma_f32_16x16x32_bf16 v[128:131], v[132:135], v[164:167], v[128:131]
	v_mfma_f32_16x16x32_bf16 v[124:127], v[140:143], v[164:167], v[124:127]
	v_mfma_f32_16x16x32_bf16 v[112:115], v[132:135], v[192:195], v[112:115]
	v_mfma_f32_16x16x32_bf16 v[108:111], v[140:143], v[192:195], v[108:111]
	v_mfma_f32_16x16x32_bf16 v[96:99], v[132:135], v[200:203], v[96:99]
	v_mfma_f32_16x16x32_bf16 v[92:95], v[140:143], v[200:203], v[92:95]
	v_mfma_f32_16x16x32_bf16 v[80:83], v[132:135], v[208:211], v[80:83]
	v_mfma_f32_16x16x32_bf16 v[76:79], v[140:143], v[208:211], v[76:79]
	v_mfma_f32_16x16x32_bf16 v[128:131], v[136:139], v[188:191], v[128:131]
	v_mfma_f32_16x16x32_bf16 v[124:127], v[144:147], v[188:191], v[124:127]
	v_mfma_f32_16x16x32_bf16 v[112:115], v[136:139], v[196:199], v[112:115]
	v_mfma_f32_16x16x32_bf16 v[108:111], v[144:147], v[196:199], v[108:111]
	v_mfma_f32_16x16x32_bf16 v[96:99], v[136:139], v[204:207], v[96:99]
	v_mfma_f32_16x16x32_bf16 v[92:95], v[144:147], v[204:207], v[92:95]
	v_mfma_f32_16x16x32_bf16 v[80:83], v[136:139], v[212:215], v[80:83]
	v_mfma_f32_16x16x32_bf16 v[76:79], v[144:147], v[212:215], v[76:79]
	v_mfma_f32_16x16x32_bf16 v[120:123], v[148:151], v[164:167], v[120:123]
	v_mfma_f32_16x16x32_bf16 v[116:119], v[156:159], v[164:167], v[116:119]
	v_mfma_f32_16x16x32_bf16 v[104:107], v[148:151], v[192:195], v[104:107]
	v_mfma_f32_16x16x32_bf16 v[100:103], v[156:159], v[192:195], v[100:103]
	v_mfma_f32_16x16x32_bf16 v[88:91], v[148:151], v[200:203], v[88:91]
	v_mfma_f32_16x16x32_bf16 v[84:87], v[156:159], v[200:203], v[84:87]
	v_mfma_f32_16x16x32_bf16 v[72:75], v[148:151], v[208:211], v[72:75]
	v_mfma_f32_16x16x32_bf16 v[68:71], v[156:159], v[208:211], v[68:71]
	v_mfma_f32_16x16x32_bf16 v[120:123], v[152:155], v[188:191], v[120:123]
	v_mfma_f32_16x16x32_bf16 v[116:119], v[160:163], v[188:191], v[116:119]
	v_mfma_f32_16x16x32_bf16 v[104:107], v[152:155], v[196:199], v[104:107]
	v_mfma_f32_16x16x32_bf16 v[100:103], v[160:163], v[196:199], v[100:103]
	v_mfma_f32_16x16x32_bf16 v[88:91], v[152:155], v[204:207], v[88:91]
	v_mfma_f32_16x16x32_bf16 v[84:87], v[160:163], v[204:207], v[84:87]
	v_mfma_f32_16x16x32_bf16 v[72:75], v[152:155], v[212:215], v[72:75]
	v_mfma_f32_16x16x32_bf16 v[68:71], v[160:163], v[212:215], v[68:71]
	s_barrier
	s_setprio 0
	s_add_i32 s16, s16, s73
	v_lshl_add_u64 v[174:175], s[28:29], 0, v[2:3]
	s_mov_b32 m0, s16
	ds_read_b128 v[164:167], v246 offset:16384
	ds_read_b128 v[188:191], v246 offset:17408
	ds_read_b128 v[192:195], v246 offset:18432
	ds_read_b128 v[196:199], v246 offset:19456
	ds_read_b128 v[200:203], v246 offset:20480
	ds_read_b128 v[204:207], v246 offset:21504
	ds_read_b128 v[208:211], v246 offset:22528
	ds_read_b128 v[212:215], v246 offset:23552
	global_load_lds_dwordx4 v[174:175], off
	s_add_i32 m0, s16, 0x2000
	s_add_u32 s16, s28, 0x58000
	v_lshl_add_u64 v[182:183], s[28:29], 0, v[168:169]
	s_addc_u32 s17, s29, 0
	s_add_i32 s23, s23, s73
	global_load_lds_dwordx4 v[182:183], off
	v_lshl_add_u64 v[216:217], s[16:17], 0, v[2:3]
	s_mov_b32 m0, s23
	v_lshl_add_u64 v[218:219], vcc, 0, v[170:171]
	global_load_lds_dwordx4 v[216:217], off
	v_lshl_add_u64 v[216:217], s[16:17], 0, v[168:169]
	s_add_i32 m0, s23, 0x2000
	s_nop 0
	global_load_lds_dwordx4 v[216:217], off
	v_lshl_add_u64 v[216:217], vcc, 0, v[172:173]
	s_mov_b32 m0, s74
	s_nop 0
	global_load_lds_dwordx4 v[216:217], off
	s_mov_b32 m0, s77
	s_nop 0
	global_load_lds_dwordx4 v[218:219], off
	s_waitcnt vmcnt(8)
	s_waitcnt lgkmcnt(0)
	s_setprio 1
	s_barrier
	v_mfma_f32_16x16x32_bf16 v[64:67], v[132:135], v[164:167], v[64:67]
	v_mfma_f32_16x16x32_bf16 v[60:63], v[140:143], v[164:167], v[60:63]
	v_mfma_f32_16x16x32_bf16 v[48:51], v[132:135], v[192:195], v[48:51]
	v_mfma_f32_16x16x32_bf16 v[44:47], v[140:143], v[192:195], v[44:47]
	v_mfma_f32_16x16x32_bf16 v[32:35], v[132:135], v[200:203], v[32:35]
	v_mfma_f32_16x16x32_bf16 v[28:31], v[140:143], v[200:203], v[28:31]
	v_mfma_f32_16x16x32_bf16 v[16:19], v[132:135], v[208:211], v[16:19]
	v_mfma_f32_16x16x32_bf16 v[12:15], v[140:143], v[208:211], v[12:15]
	v_mfma_f32_16x16x32_bf16 v[64:67], v[136:139], v[188:191], v[64:67]
	v_mfma_f32_16x16x32_bf16 v[60:63], v[144:147], v[188:191], v[60:63]
	v_mfma_f32_16x16x32_bf16 v[48:51], v[136:139], v[196:199], v[48:51]
	v_mfma_f32_16x16x32_bf16 v[44:47], v[144:147], v[196:199], v[44:47]
	v_mfma_f32_16x16x32_bf16 v[32:35], v[136:139], v[204:207], v[32:35]
	v_mfma_f32_16x16x32_bf16 v[28:31], v[144:147], v[204:207], v[28:31]
	v_mfma_f32_16x16x32_bf16 v[16:19], v[136:139], v[212:215], v[16:19]
	v_mfma_f32_16x16x32_bf16 v[12:15], v[144:147], v[212:215], v[12:15]
	v_mfma_f32_16x16x32_bf16 v[56:59], v[148:151], v[164:167], v[56:59]
	v_mfma_f32_16x16x32_bf16 v[52:55], v[156:159], v[164:167], v[52:55]
	v_mfma_f32_16x16x32_bf16 v[40:43], v[148:151], v[192:195], v[40:43]
	v_mfma_f32_16x16x32_bf16 v[36:39], v[156:159], v[192:195], v[36:39]
	v_mfma_f32_16x16x32_bf16 v[24:27], v[148:151], v[200:203], v[24:27]
	v_mfma_f32_16x16x32_bf16 v[20:23], v[156:159], v[200:203], v[20:23]
	v_mfma_f32_16x16x32_bf16 v[8:11], v[148:151], v[208:211], v[8:11]
	v_mfma_f32_16x16x32_bf16 v[4:7], v[156:159], v[208:211], v[4:7]
	v_mfma_f32_16x16x32_bf16 v[56:59], v[152:155], v[188:191], v[56:59]
	v_mfma_f32_16x16x32_bf16 v[52:55], v[160:163], v[188:191], v[52:55]
	v_mfma_f32_16x16x32_bf16 v[40:43], v[152:155], v[196:199], v[40:43]
	v_mfma_f32_16x16x32_bf16 v[36:39], v[160:163], v[196:199], v[36:39]
	v_mfma_f32_16x16x32_bf16 v[24:27], v[152:155], v[204:207], v[24:27]
	v_mfma_f32_16x16x32_bf16 v[20:23], v[160:163], v[204:207], v[20:23]
	v_mfma_f32_16x16x32_bf16 v[8:11], v[152:155], v[212:215], v[8:11]
	v_mfma_f32_16x16x32_bf16 v[4:7], v[160:163], v[212:215], v[4:7]
	s_barrier
	s_setprio 0
	s_add_i32 s23, 0, 0x18000
	s_add_i32 s50, 0, 0x1c000
	v_add_u32_e32 v144, s23, v244
	v_add_u32_e32 v160, s50, v244
	ds_read_b128 v[132:135], v144
	ds_read_b128 v[136:139], v144 offset:1024
	ds_read_b128 v[140:143], v144 offset:2048
	ds_read_b128 v[144:147], v144 offset:3072
	ds_read_b128 v[148:151], v160
	ds_read_b128 v[152:155], v160 offset:1024
	ds_read_b128 v[156:159], v160 offset:2048
	ds_read_b128 v[160:163], v160 offset:3072
	s_add_u32 s16, vcc_lo, 0x160000
	s_addc_u32 s17, vcc_hi, 0
	s_mov_b32 m0, s72
	v_lshl_add_u64 v[220:221], s[16:17], 0, v[172:173]
	ds_read_b128 v[164:167], v246 offset:32768
	ds_read_b128 v[188:191], v246 offset:33792
	ds_read_b128 v[192:195], v246 offset:34816
	ds_read_b128 v[196:199], v246 offset:35840
	ds_read_b128 v[200:203], v246 offset:36864
	ds_read_b128 v[204:207], v246 offset:37888
	ds_read_b128 v[208:211], v246 offset:38912
	ds_read_b128 v[212:215], v246 offset:39936
	global_load_lds_dwordx4 v[220:221], off
	v_lshl_add_u64 v[220:221], s[16:17], 0, v[170:171]
	s_mov_b32 m0, s78
	s_nop 0
	global_load_lds_dwordx4 v[220:221], off
	s_waitcnt vmcnt(8)
	s_waitcnt lgkmcnt(0)
	s_setprio 1
	s_barrier
	v_mfma_f32_16x16x32_bf16 v[128:131], v[132:135], v[164:167], v[128:131]
	v_mfma_f32_16x16x32_bf16 v[124:127], v[140:143], v[164:167], v[124:127]
	v_mfma_f32_16x16x32_bf16 v[112:115], v[132:135], v[192:195], v[112:115]
	v_mfma_f32_16x16x32_bf16 v[108:111], v[140:143], v[192:195], v[108:111]
	v_mfma_f32_16x16x32_bf16 v[96:99], v[132:135], v[200:203], v[96:99]
	v_mfma_f32_16x16x32_bf16 v[92:95], v[140:143], v[200:203], v[92:95]
	v_mfma_f32_16x16x32_bf16 v[80:83], v[132:135], v[208:211], v[80:83]
	v_mfma_f32_16x16x32_bf16 v[76:79], v[140:143], v[208:211], v[76:79]
	v_mfma_f32_16x16x32_bf16 v[128:131], v[136:139], v[188:191], v[128:131]
	v_mfma_f32_16x16x32_bf16 v[124:127], v[144:147], v[188:191], v[124:127]
	v_mfma_f32_16x16x32_bf16 v[112:115], v[136:139], v[196:199], v[112:115]
	v_mfma_f32_16x16x32_bf16 v[108:111], v[144:147], v[196:199], v[108:111]
	v_mfma_f32_16x16x32_bf16 v[96:99], v[136:139], v[204:207], v[96:99]
	v_mfma_f32_16x16x32_bf16 v[92:95], v[144:147], v[204:207], v[92:95]
	v_mfma_f32_16x16x32_bf16 v[80:83], v[136:139], v[212:215], v[80:83]
	v_mfma_f32_16x16x32_bf16 v[76:79], v[144:147], v[212:215], v[76:79]
	v_mfma_f32_16x16x32_bf16 v[120:123], v[148:151], v[164:167], v[120:123]
	v_mfma_f32_16x16x32_bf16 v[116:119], v[156:159], v[164:167], v[116:119]
	v_mfma_f32_16x16x32_bf16 v[104:107], v[148:151], v[192:195], v[104:107]
	v_mfma_f32_16x16x32_bf16 v[100:103], v[156:159], v[192:195], v[100:103]
	v_mfma_f32_16x16x32_bf16 v[88:91], v[148:151], v[200:203], v[88:91]
	v_mfma_f32_16x16x32_bf16 v[84:87], v[156:159], v[200:203], v[84:87]
	v_mfma_f32_16x16x32_bf16 v[72:75], v[148:151], v[208:211], v[72:75]
	v_mfma_f32_16x16x32_bf16 v[68:71], v[156:159], v[208:211], v[68:71]
	v_mfma_f32_16x16x32_bf16 v[120:123], v[152:155], v[188:191], v[120:123]
	v_mfma_f32_16x16x32_bf16 v[116:119], v[160:163], v[188:191], v[116:119]
	v_mfma_f32_16x16x32_bf16 v[104:107], v[152:155], v[196:199], v[104:107]
	v_mfma_f32_16x16x32_bf16 v[100:103], v[160:163], v[196:199], v[100:103]
	v_mfma_f32_16x16x32_bf16 v[88:91], v[152:155], v[204:207], v[88:91]
	v_mfma_f32_16x16x32_bf16 v[84:87], v[160:163], v[204:207], v[84:87]
	v_mfma_f32_16x16x32_bf16 v[72:75], v[152:155], v[212:215], v[72:75]
	v_mfma_f32_16x16x32_bf16 v[68:71], v[160:163], v[212:215], v[68:71]
	s_barrier
	s_setprio 0
	s_add_i32 s16, s23, s73
	v_lshl_add_u64 v[174:175], v[174:175], 0, s[24:25]
	s_mov_b32 m0, s16
	ds_read_b128 v[164:167], v246 offset:49152
	ds_read_b128 v[188:191], v246 offset:50176
	ds_read_b128 v[192:195], v246 offset:51200
	ds_read_b128 v[196:199], v246 offset:52224
	ds_read_b128 v[200:203], v246 offset:53248
	ds_read_b128 v[204:207], v246 offset:54272
	ds_read_b128 v[208:211], v246 offset:55296
	ds_read_b128 v[212:215], v246 offset:56320
	global_load_lds_dwordx4 v[174:175], off
	s_add_i32 m0, s16, 0x2000
	s_add_u32 s16, s28, 0x58080
	v_lshl_add_u64 v[174:175], v[182:183], 0, s[24:25]
	s_addc_u32 s17, s29, 0
	s_add_i32 s23, s50, s73
	global_load_lds_dwordx4 v[174:175], off
	v_lshl_add_u64 v[174:175], s[16:17], 0, v[2:3]
	s_mov_b32 m0, s23
	s_nop 0
	global_load_lds_dwordx4 v[174:175], off
	v_lshl_add_u64 v[174:175], s[16:17], 0, v[168:169]
	s_add_i32 m0, s23, 0x2000
	s_nop 0
	global_load_lds_dwordx4 v[174:175], off
	v_lshl_add_u64 v[174:175], v[216:217], 0, s[24:25]
	s_mov_b32 m0, s36
	s_nop 0
	global_load_lds_dwordx4 v[174:175], off
	v_lshl_add_u64 v[174:175], v[218:219], 0, s[24:25]
	s_mov_b32 m0, s37
	s_nop 0
	global_load_lds_dwordx4 v[174:175], off
	s_waitcnt vmcnt(8)
	s_waitcnt lgkmcnt(0)
	s_setprio 1
	s_barrier
	v_mfma_f32_16x16x32_bf16 v[64:67], v[132:135], v[164:167], v[64:67]
	v_mfma_f32_16x16x32_bf16 v[60:63], v[140:143], v[164:167], v[60:63]
	v_mfma_f32_16x16x32_bf16 v[48:51], v[132:135], v[192:195], v[48:51]
	v_mfma_f32_16x16x32_bf16 v[44:47], v[140:143], v[192:195], v[44:47]
	v_mfma_f32_16x16x32_bf16 v[32:35], v[132:135], v[200:203], v[32:35]
	v_mfma_f32_16x16x32_bf16 v[28:31], v[140:143], v[200:203], v[28:31]
	v_mfma_f32_16x16x32_bf16 v[16:19], v[132:135], v[208:211], v[16:19]
	v_mfma_f32_16x16x32_bf16 v[12:15], v[140:143], v[208:211], v[12:15]
	v_mfma_f32_16x16x32_bf16 v[64:67], v[136:139], v[188:191], v[64:67]
	v_mfma_f32_16x16x32_bf16 v[60:63], v[144:147], v[188:191], v[60:63]
	v_mfma_f32_16x16x32_bf16 v[48:51], v[136:139], v[196:199], v[48:51]
	v_mfma_f32_16x16x32_bf16 v[44:47], v[144:147], v[196:199], v[44:47]
	v_mfma_f32_16x16x32_bf16 v[32:35], v[136:139], v[204:207], v[32:35]
	v_mfma_f32_16x16x32_bf16 v[28:31], v[144:147], v[204:207], v[28:31]
	v_mfma_f32_16x16x32_bf16 v[16:19], v[136:139], v[212:215], v[16:19]
	v_mfma_f32_16x16x32_bf16 v[12:15], v[144:147], v[212:215], v[12:15]
	v_mfma_f32_16x16x32_bf16 v[56:59], v[148:151], v[164:167], v[56:59]
	v_mfma_f32_16x16x32_bf16 v[52:55], v[156:159], v[164:167], v[52:55]
	v_mfma_f32_16x16x32_bf16 v[40:43], v[148:151], v[192:195], v[40:43]
	v_mfma_f32_16x16x32_bf16 v[36:39], v[156:159], v[192:195], v[36:39]
	v_mfma_f32_16x16x32_bf16 v[24:27], v[148:151], v[200:203], v[24:27]
	v_mfma_f32_16x16x32_bf16 v[20:23], v[156:159], v[200:203], v[20:23]
	v_mfma_f32_16x16x32_bf16 v[8:11], v[148:151], v[208:211], v[8:11]
	v_mfma_f32_16x16x32_bf16 v[4:7], v[156:159], v[208:211], v[4:7]
	v_mfma_f32_16x16x32_bf16 v[56:59], v[152:155], v[188:191], v[56:59]
	v_mfma_f32_16x16x32_bf16 v[52:55], v[160:163], v[188:191], v[52:55]
	v_mfma_f32_16x16x32_bf16 v[40:43], v[152:155], v[196:199], v[40:43]
	v_mfma_f32_16x16x32_bf16 v[36:39], v[160:163], v[196:199], v[36:39]
	v_mfma_f32_16x16x32_bf16 v[24:27], v[152:155], v[204:207], v[24:27]
	v_mfma_f32_16x16x32_bf16 v[20:23], v[160:163], v[204:207], v[20:23]
	v_mfma_f32_16x16x32_bf16 v[8:11], v[152:155], v[212:215], v[8:11]
	v_mfma_f32_16x16x32_bf16 v[4:7], v[160:163], v[212:215], v[4:7]
	s_barrier
	s_setprio 0
	s_add_i32 s22, s22, 2
	s_add_u32 s31, s31, 0x100
	s_addc_u32 s33, s33, 0
	s_cmpk_gt_u32 s22, 0x55
	s_mov_b64 s[50:51], s[48:49]
	s_cbranch_scc0 .LBB0_366
	v_readlane_b32 s16, v252, 12
	v_readlane_b32 s17, v252, 13

.LBB0_445:
	s_ashr_i32 s37, s36, 31
	s_lshl_b64 s[16:17], s[36:37], 20
	s_add_u32 s40, s0, s16
	s_addc_u32 s41, s1, s17
	s_and_b64 s[16:17], s[38:39], exec
	s_cselect_b32 s37, s41, s45
	s_cselect_b32 s88, s40, s44
	s_ashr_i32 s27, s26, 31
	s_lshl_b64 s[16:17], s[26:27], 20
	s_add_u32 s42, s3, s16
	s_addc_u32 s43, s31, s17
	s_and_b64 s[16:17], s[38:39], exec
	s_cselect_b32 s27, s43, s29
	s_cselect_b32 s89, s42, s28
	s_add_u32 s44, s44, 0x80080
	s_addc_u32 s45, s45, 0
	s_add_u32 s91, s28, 0x100
	v_mov_b32_e32 v235, 0x42000000
	v_mov_b32_e32 v233, 0x400
	v_mov_b64_e32 v[240:241], 0x1080
	s_addc_u32 s96, s29, 0
	s_mov_b32 vcc_lo, -2
	s_waitcnt lgkmcnt(0)
	s_waitcnt vmcnt(0)
	s_add_u32 s16, s44, 0xfff80080
	s_addc_u32 s17, s45, -1
	s_add_i32 s94, 0, 0x10000
	s_cmp_eq_u32 vcc_lo, 28
	s_cselect_b32 s47, s37, s17
	s_cselect_b32 s46, s88, s16
	s_cselect_b32 s29, s27, s96
	s_cselect_b32 s28, s89, s91
	s_add_i32 s95, 0, 0x14000
	v_add_u32_e32 v144, s94, v219
	v_add_u32_e32 v172, s95, v219
	ds_read_b128 v[132:135], v144
	ds_read_b128 v[136:139], v144 offset:1024
	ds_read_b128 v[140:143], v144 offset:2048
	ds_read_b128 v[144:147], v144 offset:3072
	ds_read_b128 v[148:151], v172
	ds_read_b128 v[164:167], v172 offset:1024
	ds_read_b128 v[168:171], v172 offset:2048
	ds_read_b128 v[184:187], v172 offset:3072
	v_lshl_add_u64 v[172:173], s[44:45], 0, v[160:161]
	s_add_i32 m0, s48, 0xc000
	ds_read_b128 v[188:191], v221
	ds_read_b128 v[192:195], v221 offset:1024
	ds_read_b128 v[196:199], v221 offset:2048
	ds_read_b128 v[200:203], v221 offset:3072
	ds_read_b128 v[204:207], v221 offset:4096
	ds_read_b128 v[208:211], v221 offset:5120
	ds_read_b128 v[212:215], v221 offset:6144
	ds_read_b128 v[222:225], v221 offset:7168
	global_load_lds_dwordx4 v[172:173], off
	v_lshl_add_u64 v[172:173], s[44:45], 0, v[162:163]
	s_add_i32 m0, s48, 0xe000
	s_nop 0
	global_load_lds_dwordx4 v[172:173], off
	v_mov_b32_e32 v4, 0
	v_mov_b32_e32 v5, v4
	v_mov_b32_e32 v6, v4
	v_mov_b32_e32 v7, v4
	v_mov_b32_e32 v8, v4
	v_mov_b32_e32 v9, v4
	v_mov_b32_e32 v10, v4
	v_mov_b32_e32 v11, v4
	v_mov_b32_e32 v20, v4
	v_mov_b32_e32 v21, v4
	v_mov_b32_e32 v22, v4
	v_mov_b32_e32 v23, v4
	v_mov_b32_e32 v24, v4
	v_mov_b32_e32 v25, v4
	v_mov_b32_e32 v26, v4
	v_mov_b32_e32 v27, v4
	v_mov_b32_e32 v36, v4
	v_mov_b32_e32 v37, v4
	v_mov_b32_e32 v38, v4
	v_mov_b32_e32 v39, v4
	v_mov_b32_e32 v40, v4
	v_mov_b32_e32 v41, v4
	v_mov_b32_e32 v42, v4
	v_mov_b32_e32 v43, v4
	v_mov_b32_e32 v52, v4
	v_mov_b32_e32 v53, v4
	v_mov_b32_e32 v54, v4
	v_mov_b32_e32 v55, v4
	v_mov_b32_e32 v56, v4
	v_mov_b32_e32 v57, v4
	v_mov_b32_e32 v58, v4
	v_mov_b32_e32 v59, v4
	v_mov_b32_e32 v12, v4
	v_mov_b32_e32 v13, v4
	v_mov_b32_e32 v14, v4
	v_mov_b32_e32 v15, v4
	v_mov_b32_e32 v16, v4
	v_mov_b32_e32 v17, v4
	v_mov_b32_e32 v18, v4
	v_mov_b32_e32 v19, v4
	v_mov_b32_e32 v28, v4
	v_mov_b32_e32 v29, v4
	v_mov_b32_e32 v30, v4
	v_mov_b32_e32 v31, v4
	v_mov_b32_e32 v32, v4
	v_mov_b32_e32 v33, v4
	v_mov_b32_e32 v34, v4
	v_mov_b32_e32 v35, v4
	v_mov_b32_e32 v44, v4
	v_mov_b32_e32 v45, v4
	v_mov_b32_e32 v46, v4
	v_mov_b32_e32 v47, v4
	v_mov_b32_e32 v48, v4
	v_mov_b32_e32 v49, v4
	v_mov_b32_e32 v50, v4
	v_mov_b32_e32 v51, v4
	v_mov_b32_e32 v60, v4
	v_mov_b32_e32 v61, v4
	v_mov_b32_e32 v62, v4
	v_mov_b32_e32 v63, v4
	v_mov_b32_e32 v64, v4
	v_mov_b32_e32 v65, v4
	v_mov_b32_e32 v66, v4
	v_mov_b32_e32 v67, v4
	v_mov_b32_e32 v68, v4
	v_mov_b32_e32 v69, v4
	v_mov_b32_e32 v70, v4
	v_mov_b32_e32 v71, v4
	v_mov_b32_e32 v72, v4
	v_mov_b32_e32 v73, v4
	v_mov_b32_e32 v74, v4
	v_mov_b32_e32 v75, v4
	v_mov_b32_e32 v84, v4
	v_mov_b32_e32 v85, v4
	v_mov_b32_e32 v86, v4
	v_mov_b32_e32 v87, v4
	v_mov_b32_e32 v88, v4
	v_mov_b32_e32 v89, v4
	v_mov_b32_e32 v90, v4
	v_mov_b32_e32 v91, v4
	v_mov_b32_e32 v100, v4
	v_mov_b32_e32 v101, v4
	v_mov_b32_e32 v102, v4
	v_mov_b32_e32 v103, v4
	v_mov_b32_e32 v104, v4
	v_mov_b32_e32 v105, v4
	v_mov_b32_e32 v106, v4
	v_mov_b32_e32 v107, v4
	v_mov_b32_e32 v116, v4
	v_mov_b32_e32 v117, v4
	v_mov_b32_e32 v118, v4
	v_mov_b32_e32 v119, v4
	v_mov_b32_e32 v120, v4
	v_mov_b32_e32 v121, v4
	v_mov_b32_e32 v122, v4
	v_mov_b32_e32 v123, v4
	v_mov_b32_e32 v76, v4
	v_mov_b32_e32 v77, v4
	v_mov_b32_e32 v78, v4
	v_mov_b32_e32 v79, v4
	v_mov_b32_e32 v80, v4
	v_mov_b32_e32 v81, v4
	v_mov_b32_e32 v82, v4
	v_mov_b32_e32 v83, v4
	v_mov_b32_e32 v92, v4
	v_mov_b32_e32 v93, v4
	v_mov_b32_e32 v94, v4
	v_mov_b32_e32 v95, v4
	v_mov_b32_e32 v96, v4
	v_mov_b32_e32 v97, v4
	v_mov_b32_e32 v98, v4
	v_mov_b32_e32 v99, v4
	v_mov_b32_e32 v108, v4
	v_mov_b32_e32 v109, v4
	v_mov_b32_e32 v110, v4
	v_mov_b32_e32 v111, v4
	v_mov_b32_e32 v112, v4
	v_mov_b32_e32 v113, v4
	v_mov_b32_e32 v114, v4
	v_mov_b32_e32 v115, v4
	v_mov_b32_e32 v124, v4
	v_mov_b32_e32 v125, v4
	v_mov_b32_e32 v126, v4
	v_mov_b32_e32 v127, v4
	v_mov_b32_e32 v128, v4
	v_mov_b32_e32 v129, v4
	v_mov_b32_e32 v130, v4
	v_mov_b32_e32 v131, v4
	s_branch .Lmid_446

.Lmid_446:
	s_waitcnt vmcnt(8)
	s_waitcnt lgkmcnt(0)
	s_setprio 1
	s_barrier
	v_mfma_f32_16x16x32_bf16 v[128:131], v[132:135], v[188:191], v[128:131]
	v_mfma_f32_16x16x32_bf16 v[124:127], v[140:143], v[188:191], v[124:127]
	v_mfma_f32_16x16x32_bf16 v[112:115], v[132:135], v[196:199], v[112:115]
	v_mfma_f32_16x16x32_bf16 v[108:111], v[140:143], v[196:199], v[108:111]
	v_mfma_f32_16x16x32_bf16 v[96:99], v[132:135], v[204:207], v[96:99]
	v_mfma_f32_16x16x32_bf16 v[92:95], v[140:143], v[204:207], v[92:95]
	v_mfma_f32_16x16x32_bf16 v[80:83], v[132:135], v[212:215], v[80:83]
	v_mfma_f32_16x16x32_bf16 v[76:79], v[140:143], v[212:215], v[76:79]
	v_mfma_f32_16x16x32_bf16 v[128:131], v[136:139], v[192:195], v[128:131]
	v_mfma_f32_16x16x32_bf16 v[124:127], v[144:147], v[192:195], v[124:127]
	v_mfma_f32_16x16x32_bf16 v[112:115], v[136:139], v[200:203], v[112:115]
	v_mfma_f32_16x16x32_bf16 v[108:111], v[144:147], v[200:203], v[108:111]
	v_mfma_f32_16x16x32_bf16 v[96:99], v[136:139], v[208:211], v[96:99]
	v_mfma_f32_16x16x32_bf16 v[92:95], v[144:147], v[208:211], v[92:95]
	v_mfma_f32_16x16x32_bf16 v[80:83], v[136:139], v[222:225], v[80:83]
	v_mfma_f32_16x16x32_bf16 v[76:79], v[144:147], v[222:225], v[76:79]
	v_mfma_f32_16x16x32_bf16 v[120:123], v[148:151], v[188:191], v[120:123]
	v_mfma_f32_16x16x32_bf16 v[116:119], v[168:171], v[188:191], v[116:119]
	v_mfma_f32_16x16x32_bf16 v[104:107], v[148:151], v[196:199], v[104:107]
	v_mfma_f32_16x16x32_bf16 v[100:103], v[168:171], v[196:199], v[100:103]
	v_mfma_f32_16x16x32_bf16 v[88:91], v[148:151], v[204:207], v[88:91]
	v_mfma_f32_16x16x32_bf16 v[84:87], v[168:171], v[204:207], v[84:87]
	v_mfma_f32_16x16x32_bf16 v[72:75], v[148:151], v[212:215], v[72:75]
	v_mfma_f32_16x16x32_bf16 v[68:71], v[168:171], v[212:215], v[68:71]
	v_mfma_f32_16x16x32_bf16 v[120:123], v[164:167], v[192:195], v[120:123]
	v_mfma_f32_16x16x32_bf16 v[116:119], v[184:187], v[192:195], v[116:119]
	v_mfma_f32_16x16x32_bf16 v[104:107], v[164:167], v[200:203], v[104:107]
	v_mfma_f32_16x16x32_bf16 v[100:103], v[184:187], v[200:203], v[100:103]
	v_mfma_f32_16x16x32_bf16 v[88:91], v[164:167], v[208:211], v[88:91]
	v_mfma_f32_16x16x32_bf16 v[84:87], v[184:187], v[208:211], v[84:87]
	v_mfma_f32_16x16x32_bf16 v[72:75], v[164:167], v[222:225], v[72:75]
	v_mfma_f32_16x16x32_bf16 v[68:71], v[184:187], v[222:225], v[68:71]
	s_barrier
	s_setprio 0
	s_add_i32 s16, s94, s33
	v_lshl_add_u64 v[172:173], s[28:29], 0, v[2:3]
	s_mov_b32 m0, s16
	ds_read_b128 v[188:191], v221 offset:16384
	ds_read_b128 v[192:195], v221 offset:17408
	ds_read_b128 v[196:199], v221 offset:18432
	ds_read_b128 v[200:203], v221 offset:19456
	ds_read_b128 v[204:207], v221 offset:20480
	ds_read_b128 v[208:211], v221 offset:21504
	ds_read_b128 v[212:215], v221 offset:22528
	ds_read_b128 v[222:225], v221 offset:23552
	global_load_lds_dwordx4 v[172:173], off
	s_add_i32 m0, s16, 0x2000
	s_add_u32 s16, s28, 0x80000
	v_lshl_add_u64 v[174:175], s[28:29], 0, v[152:153]
	s_addc_u32 s17, s29, 0
	s_add_i32 s94, s95, s33
	global_load_lds_dwordx4 v[174:175], off
	v_lshl_add_u64 v[182:183], s[16:17], 0, v[2:3]
	s_mov_b32 m0, s94
	v_lshl_add_u64 v[216:217], s[46:47], 0, v[154:155]
	global_load_lds_dwordx4 v[182:183], off
	v_lshl_add_u64 v[182:183], s[16:17], 0, v[152:153]
	s_add_i32 m0, s94, 0x2000
	s_nop 0
	global_load_lds_dwordx4 v[182:183], off
	v_lshl_add_u64 v[182:183], s[46:47], 0, v[156:157]
	s_mov_b32 m0, s48
	s_nop 0
	global_load_lds_dwordx4 v[182:183], off
	s_mov_b32 m0, s49
	s_nop 0
	global_load_lds_dwordx4 v[216:217], off
	s_waitcnt vmcnt(8)
	s_waitcnt lgkmcnt(0)
	s_setprio 1
	s_barrier
	v_mfma_f32_16x16x32_bf16 v[64:67], v[132:135], v[188:191], v[64:67]
	v_mfma_f32_16x16x32_bf16 v[60:63], v[140:143], v[188:191], v[60:63]
	v_mfma_f32_16x16x32_bf16 v[48:51], v[132:135], v[196:199], v[48:51]
	v_mfma_f32_16x16x32_bf16 v[44:47], v[140:143], v[196:199], v[44:47]
	v_mfma_f32_16x16x32_bf16 v[32:35], v[132:135], v[204:207], v[32:35]
	v_mfma_f32_16x16x32_bf16 v[28:31], v[140:143], v[204:207], v[28:31]
	v_mfma_f32_16x16x32_bf16 v[16:19], v[132:135], v[212:215], v[16:19]
	v_mfma_f32_16x16x32_bf16 v[12:15], v[140:143], v[212:215], v[12:15]
	v_mfma_f32_16x16x32_bf16 v[64:67], v[136:139], v[192:195], v[64:67]
	v_mfma_f32_16x16x32_bf16 v[60:63], v[144:147], v[192:195], v[60:63]
	v_mfma_f32_16x16x32_bf16 v[48:51], v[136:139], v[200:203], v[48:51]
	v_mfma_f32_16x16x32_bf16 v[44:47], v[144:147], v[200:203], v[44:47]
	v_mfma_f32_16x16x32_bf16 v[32:35], v[136:139], v[208:211], v[32:35]
	v_mfma_f32_16x16x32_bf16 v[28:31], v[144:147], v[208:211], v[28:31]
	v_mfma_f32_16x16x32_bf16 v[16:19], v[136:139], v[222:225], v[16:19]
	v_mfma_f32_16x16x32_bf16 v[12:15], v[144:147], v[222:225], v[12:15]
	v_mfma_f32_16x16x32_bf16 v[56:59], v[148:151], v[188:191], v[56:59]
	v_mfma_f32_16x16x32_bf16 v[52:55], v[168:171], v[188:191], v[52:55]
	v_mfma_f32_16x16x32_bf16 v[40:43], v[148:151], v[196:199], v[40:43]
	v_mfma_f32_16x16x32_bf16 v[36:39], v[168:171], v[196:199], v[36:39]
	v_mfma_f32_16x16x32_bf16 v[24:27], v[148:151], v[204:207], v[24:27]
	v_mfma_f32_16x16x32_bf16 v[20:23], v[168:171], v[204:207], v[20:23]
	v_mfma_f32_16x16x32_bf16 v[8:11], v[148:151], v[212:215], v[8:11]
	v_mfma_f32_16x16x32_bf16 v[4:7], v[168:171], v[212:215], v[4:7]
	v_mfma_f32_16x16x32_bf16 v[56:59], v[164:167], v[192:195], v[56:59]
	v_mfma_f32_16x16x32_bf16 v[52:55], v[184:187], v[192:195], v[52:55]
	v_mfma_f32_16x16x32_bf16 v[40:43], v[164:167], v[200:203], v[40:43]
	v_mfma_f32_16x16x32_bf16 v[36:39], v[184:187], v[200:203], v[36:39]
	v_mfma_f32_16x16x32_bf16 v[24:27], v[164:167], v[208:211], v[24:27]
	v_mfma_f32_16x16x32_bf16 v[20:23], v[184:187], v[208:211], v[20:23]
	v_mfma_f32_16x16x32_bf16 v[8:11], v[164:167], v[222:225], v[8:11]
	v_mfma_f32_16x16x32_bf16 v[4:7], v[184:187], v[222:225], v[4:7]
	s_barrier
	s_setprio 0
	s_add_i32 s94, 0, 0x18000
	s_add_i32 s95, 0, 0x1c000
	v_add_u32_e32 v144, s94, v219
	v_add_u32_e32 v176, s95, v219
	ds_read_b128 v[132:135], v144
	ds_read_b128 v[136:139], v144 offset:1024
	ds_read_b128 v[140:143], v144 offset:2048
	ds_read_b128 v[144:147], v144 offset:3072
	ds_read_b128 v[148:151], v176
	ds_read_b128 v[164:167], v176 offset:1024
	ds_read_b128 v[168:171], v176 offset:2048
	ds_read_b128 v[184:187], v176 offset:3072
	s_add_u32 s16, s46, 0x80000
	s_addc_u32 s17, s47, 0
	s_mov_b32 m0, s50
	v_lshl_add_u64 v[226:227], s[16:17], 0, v[156:157]
	ds_read_b128 v[188:191], v221 offset:32768
	ds_read_b128 v[192:195], v221 offset:33792
	ds_read_b128 v[196:199], v221 offset:34816
	ds_read_b128 v[200:203], v221 offset:35840
	ds_read_b128 v[204:207], v221 offset:36864
	ds_read_b128 v[208:211], v221 offset:37888
	ds_read_b128 v[212:215], v221 offset:38912
	ds_read_b128 v[222:225], v221 offset:39936
	global_load_lds_dwordx4 v[226:227], off
	v_lshl_add_u64 v[226:227], s[16:17], 0, v[154:155]
	s_mov_b32 m0, s51
	s_nop 0
	global_load_lds_dwordx4 v[226:227], off
	s_waitcnt vmcnt(8)
	s_waitcnt lgkmcnt(0)
	s_setprio 1
	s_barrier
	v_mfma_f32_16x16x32_bf16 v[128:131], v[132:135], v[188:191], v[128:131]
	v_mfma_f32_16x16x32_bf16 v[124:127], v[140:143], v[188:191], v[124:127]
	v_mfma_f32_16x16x32_bf16 v[112:115], v[132:135], v[196:199], v[112:115]
	v_mfma_f32_16x16x32_bf16 v[108:111], v[140:143], v[196:199], v[108:111]
	v_mfma_f32_16x16x32_bf16 v[96:99], v[132:135], v[204:207], v[96:99]
	v_mfma_f32_16x16x32_bf16 v[92:95], v[140:143], v[204:207], v[92:95]
	v_mfma_f32_16x16x32_bf16 v[80:83], v[132:135], v[212:215], v[80:83]
	v_mfma_f32_16x16x32_bf16 v[76:79], v[140:143], v[212:215], v[76:79]
	v_mfma_f32_16x16x32_bf16 v[128:131], v[136:139], v[192:195], v[128:131]
	v_mfma_f32_16x16x32_bf16 v[124:127], v[144:147], v[192:195], v[124:127]
	v_mfma_f32_16x16x32_bf16 v[112:115], v[136:139], v[200:203], v[112:115]
	v_mfma_f32_16x16x32_bf16 v[108:111], v[144:147], v[200:203], v[108:111]
	v_mfma_f32_16x16x32_bf16 v[96:99], v[136:139], v[208:211], v[96:99]
	v_mfma_f32_16x16x32_bf16 v[92:95], v[144:147], v[208:211], v[92:95]
	v_mfma_f32_16x16x32_bf16 v[80:83], v[136:139], v[222:225], v[80:83]
	v_mfma_f32_16x16x32_bf16 v[76:79], v[144:147], v[222:225], v[76:79]
	v_mfma_f32_16x16x32_bf16 v[120:123], v[148:151], v[188:191], v[120:123]
	v_mfma_f32_16x16x32_bf16 v[116:119], v[168:171], v[188:191], v[116:119]
	v_mfma_f32_16x16x32_bf16 v[104:107], v[148:151], v[196:199], v[104:107]
	v_mfma_f32_16x16x32_bf16 v[100:103], v[168:171], v[196:199], v[100:103]
	v_mfma_f32_16x16x32_bf16 v[88:91], v[148:151], v[204:207], v[88:91]
	v_mfma_f32_16x16x32_bf16 v[84:87], v[168:171], v[204:207], v[84:87]
	v_mfma_f32_16x16x32_bf16 v[72:75], v[148:151], v[212:215], v[72:75]
	v_mfma_f32_16x16x32_bf16 v[68:71], v[168:171], v[212:215], v[68:71]
	v_mfma_f32_16x16x32_bf16 v[120:123], v[164:167], v[192:195], v[120:123]
	v_mfma_f32_16x16x32_bf16 v[116:119], v[184:187], v[192:195], v[116:119]
	v_mfma_f32_16x16x32_bf16 v[104:107], v[164:167], v[200:203], v[104:107]
	v_mfma_f32_16x16x32_bf16 v[100:103], v[184:187], v[200:203], v[100:103]
	v_mfma_f32_16x16x32_bf16 v[88:91], v[164:167], v[208:211], v[88:91]
	v_mfma_f32_16x16x32_bf16 v[84:87], v[184:187], v[208:211], v[84:87]
	v_mfma_f32_16x16x32_bf16 v[72:75], v[164:167], v[222:225], v[72:75]
	v_mfma_f32_16x16x32_bf16 v[68:71], v[184:187], v[222:225], v[68:71]
	s_barrier
	s_setprio 0
	s_add_i32 s16, s94, s33
	v_lshl_add_u64 v[172:173], v[172:173], 0, s[24:25]
	s_mov_b32 m0, s16
	ds_read_b128 v[188:191], v221 offset:49152
	ds_read_b128 v[192:195], v221 offset:50176
	ds_read_b128 v[196:199], v221 offset:51200
	ds_read_b128 v[200:203], v221 offset:52224
	ds_read_b128 v[204:207], v221 offset:53248
	ds_read_b128 v[208:211], v221 offset:54272
	ds_read_b128 v[212:215], v221 offset:55296
	ds_read_b128 v[222:225], v221 offset:56320
	global_load_lds_dwordx4 v[172:173], off
	s_add_i32 m0, s16, 0x2000
	s_add_u32 s16, s28, 0x80080
	v_lshl_add_u64 v[172:173], v[174:175], 0, s[24:25]
	s_addc_u32 s17, s29, 0
	s_add_i32 s28, s95, s33
	global_load_lds_dwordx4 v[172:173], off
	v_lshl_add_u64 v[172:173], s[16:17], 0, v[2:3]
	s_mov_b32 m0, s28
	s_nop 0
	global_load_lds_dwordx4 v[172:173], off
	v_lshl_add_u64 v[172:173], s[16:17], 0, v[152:153]
	s_add_i32 m0, s28, 0x2000
	s_nop 0
	global_load_lds_dwordx4 v[172:173], off
	v_lshl_add_u64 v[172:173], v[182:183], 0, s[24:25]
	s_mov_b32 m0, s72
	s_nop 0
	global_load_lds_dwordx4 v[172:173], off
	v_lshl_add_u64 v[172:173], v[216:217], 0, s[24:25]
	s_mov_b32 m0, s73
	s_nop 0
	global_load_lds_dwordx4 v[172:173], off
	s_waitcnt vmcnt(8)
	s_waitcnt lgkmcnt(0)
	s_setprio 1
	s_barrier
	v_mfma_f32_16x16x32_bf16 v[64:67], v[132:135], v[188:191], v[64:67]
	v_mfma_f32_16x16x32_bf16 v[60:63], v[140:143], v[188:191], v[60:63]
	v_mfma_f32_16x16x32_bf16 v[48:51], v[132:135], v[196:199], v[48:51]
	v_mfma_f32_16x16x32_bf16 v[44:47], v[140:143], v[196:199], v[44:47]
	v_mfma_f32_16x16x32_bf16 v[32:35], v[132:135], v[204:207], v[32:35]
	v_mfma_f32_16x16x32_bf16 v[28:31], v[140:143], v[204:207], v[28:31]
	v_mfma_f32_16x16x32_bf16 v[16:19], v[132:135], v[212:215], v[16:19]
	v_mfma_f32_16x16x32_bf16 v[12:15], v[140:143], v[212:215], v[12:15]
	v_mfma_f32_16x16x32_bf16 v[64:67], v[136:139], v[192:195], v[64:67]
	v_mfma_f32_16x16x32_bf16 v[60:63], v[144:147], v[192:195], v[60:63]
	v_mfma_f32_16x16x32_bf16 v[48:51], v[136:139], v[200:203], v[48:51]
	v_mfma_f32_16x16x32_bf16 v[44:47], v[144:147], v[200:203], v[44:47]
	v_mfma_f32_16x16x32_bf16 v[32:35], v[136:139], v[208:211], v[32:35]
	v_mfma_f32_16x16x32_bf16 v[28:31], v[144:147], v[208:211], v[28:31]
	v_mfma_f32_16x16x32_bf16 v[16:19], v[136:139], v[222:225], v[16:19]
	v_mfma_f32_16x16x32_bf16 v[12:15], v[144:147], v[222:225], v[12:15]
	v_mfma_f32_16x16x32_bf16 v[56:59], v[148:151], v[188:191], v[56:59]
	v_mfma_f32_16x16x32_bf16 v[52:55], v[168:171], v[188:191], v[52:55]
	v_mfma_f32_16x16x32_bf16 v[40:43], v[148:151], v[196:199], v[40:43]
	v_mfma_f32_16x16x32_bf16 v[36:39], v[168:171], v[196:199], v[36:39]
	v_mfma_f32_16x16x32_bf16 v[24:27], v[148:151], v[204:207], v[24:27]
	v_mfma_f32_16x16x32_bf16 v[20:23], v[168:171], v[204:207], v[20:23]
	v_mfma_f32_16x16x32_bf16 v[8:11], v[148:151], v[212:215], v[8:11]
	v_mfma_f32_16x16x32_bf16 v[4:7], v[168:171], v[212:215], v[4:7]
	v_mfma_f32_16x16x32_bf16 v[56:59], v[164:167], v[192:195], v[56:59]
	v_mfma_f32_16x16x32_bf16 v[52:55], v[184:187], v[192:195], v[52:55]
	v_mfma_f32_16x16x32_bf16 v[40:43], v[164:167], v[200:203], v[40:43]
	v_mfma_f32_16x16x32_bf16 v[36:39], v[184:187], v[200:203], v[36:39]
	v_mfma_f32_16x16x32_bf16 v[24:27], v[164:167], v[208:211], v[24:27]
	v_mfma_f32_16x16x32_bf16 v[20:23], v[184:187], v[208:211], v[20:23]
	v_mfma_f32_16x16x32_bf16 v[8:11], v[164:167], v[222:225], v[8:11]
	v_mfma_f32_16x16x32_bf16 v[4:7], v[184:187], v[222:225], v[4:7]
	s_barrier
	s_setprio 0
	s_add_i32 vcc_lo, vcc_lo, 2
	s_add_u32 s44, s44, 0x100
	s_addc_u32 s45, s45, 0
	s_add_u32 s91, s91, 0x100
	s_addc_u32 s96, s96, 0
	s_cmp_gt_u32 vcc_lo, 29
	s_cbranch_scc0 .LBB0_446
	v_mov_b32_e32 v250, 0xc2000000
	v_mov_b32_e32 v1, 0xbfb8aa3b
	v_mov_b64_e32 v[238:239], v[236:237]

.LBB0_789:
	s_ashr_i32 s19, s18, 31
	s_lshl_b64 s[10:11], s[18:19], 20
	v_readlane_b32 s16, v252, 15
	s_add_u32 s50, s16, s10
	v_readlane_b32 s10, v252, 16
	s_addc_u32 s51, s10, s11
	s_and_b64 s[10:11], s[46:47], exec
	s_cselect_b32 s19, s51, s73
	s_cselect_b32 s31, s50, s72
	s_ashr_i32 s23, s22, 31
	s_lshl_b64 s[10:11], s[22:23], 20
	s_add_u32 s26, s36, s10
	s_addc_u32 s27, s37, s11
	s_and_b64 s[10:11], s[46:47], exec
	s_cselect_b32 s23, s27, s29
	s_cselect_b32 s33, s26, s28
	s_add_u32 vcc_lo, s72, 0x80080
	s_addc_u32 vcc_hi, s73, 0
	s_add_u32 s48, s28, 0x100
	s_addc_u32 s49, s29, 0
	s_mov_b32 s10, -2
	s_waitcnt lgkmcnt(0)
	s_waitcnt vmcnt(0)
	s_add_u32 s11, vcc_lo, 0xfff80080
	s_addc_u32 s16, vcc_hi, -1
	s_add_i32 s17, 0, 0x10000
	s_cmp_eq_u32 s10, 28
	s_cselect_b32 s73, s19, s16
	s_cselect_b32 s72, s31, s11
	s_cselect_b32 s29, s23, s49
	s_cselect_b32 s28, s33, s48
	s_add_i32 s11, 0, 0x14000
	v_add_u32_e32 v144, s17, v244
	v_add_u32_e32 v160, s11, v244
	ds_read_b128 v[132:135], v144
	ds_read_b128 v[136:139], v144 offset:1024
	ds_read_b128 v[140:143], v144 offset:2048
	ds_read_b128 v[144:147], v144 offset:3072
	ds_read_b128 v[148:151], v160
	ds_read_b128 v[152:155], v160 offset:1024
	ds_read_b128 v[156:159], v160 offset:2048
	ds_read_b128 v[160:163], v160 offset:3072
	v_lshl_add_u64 v[174:175], vcc, 0, v[184:185]
	s_add_i32 m0, s77, 0xc000
	ds_read_b128 v[164:167], v246
	ds_read_b128 v[188:191], v246 offset:1024
	ds_read_b128 v[192:195], v246 offset:2048
	ds_read_b128 v[196:199], v246 offset:3072
	ds_read_b128 v[200:203], v246 offset:4096
	ds_read_b128 v[204:207], v246 offset:5120
	ds_read_b128 v[208:211], v246 offset:6144
	ds_read_b128 v[212:215], v246 offset:7168
	global_load_lds_dwordx4 v[174:175], off
	v_lshl_add_u64 v[174:175], vcc, 0, v[186:187]
	s_add_i32 m0, s77, 0xe000
	s_nop 0
	global_load_lds_dwordx4 v[174:175], off
	v_mov_b32_e32 v4, 0
	v_mov_b32_e32 v5, v4
	v_mov_b32_e32 v6, v4
	v_mov_b32_e32 v7, v4
	v_mov_b32_e32 v8, v4
	v_mov_b32_e32 v9, v4
	v_mov_b32_e32 v10, v4
	v_mov_b32_e32 v11, v4
	v_mov_b32_e32 v20, v4
	v_mov_b32_e32 v21, v4
	v_mov_b32_e32 v22, v4
	v_mov_b32_e32 v23, v4
	v_mov_b32_e32 v24, v4
	v_mov_b32_e32 v25, v4
	v_mov_b32_e32 v26, v4
	v_mov_b32_e32 v27, v4
	v_mov_b32_e32 v36, v4
	v_mov_b32_e32 v37, v4
	v_mov_b32_e32 v38, v4
	v_mov_b32_e32 v39, v4
	v_mov_b32_e32 v40, v4
	v_mov_b32_e32 v41, v4
	v_mov_b32_e32 v42, v4
	v_mov_b32_e32 v43, v4
	v_mov_b32_e32 v52, v4
	v_mov_b32_e32 v53, v4
	v_mov_b32_e32 v54, v4
	v_mov_b32_e32 v55, v4
	v_mov_b32_e32 v56, v4
	v_mov_b32_e32 v57, v4
	v_mov_b32_e32 v58, v4
	v_mov_b32_e32 v59, v4
	v_mov_b32_e32 v12, v4
	v_mov_b32_e32 v13, v4
	v_mov_b32_e32 v14, v4
	v_mov_b32_e32 v15, v4
	v_mov_b32_e32 v16, v4
	v_mov_b32_e32 v17, v4
	v_mov_b32_e32 v18, v4
	v_mov_b32_e32 v19, v4
	v_mov_b32_e32 v28, v4
	v_mov_b32_e32 v29, v4
	v_mov_b32_e32 v30, v4
	v_mov_b32_e32 v31, v4
	v_mov_b32_e32 v32, v4
	v_mov_b32_e32 v33, v4
	v_mov_b32_e32 v34, v4
	v_mov_b32_e32 v35, v4
	v_mov_b32_e32 v44, v4
	v_mov_b32_e32 v45, v4
	v_mov_b32_e32 v46, v4
	v_mov_b32_e32 v47, v4
	v_mov_b32_e32 v48, v4
	v_mov_b32_e32 v49, v4
	v_mov_b32_e32 v50, v4
	v_mov_b32_e32 v51, v4
	v_mov_b32_e32 v60, v4
	v_mov_b32_e32 v61, v4
	v_mov_b32_e32 v62, v4
	v_mov_b32_e32 v63, v4
	v_mov_b32_e32 v64, v4
	v_mov_b32_e32 v65, v4
	v_mov_b32_e32 v66, v4
	v_mov_b32_e32 v67, v4
	v_mov_b32_e32 v68, v4
	v_mov_b32_e32 v69, v4
	v_mov_b32_e32 v70, v4
	v_mov_b32_e32 v71, v4
	v_mov_b32_e32 v72, v4
	v_mov_b32_e32 v73, v4
	v_mov_b32_e32 v74, v4
	v_mov_b32_e32 v75, v4
	v_mov_b32_e32 v84, v4
	v_mov_b32_e32 v85, v4
	v_mov_b32_e32 v86, v4
	v_mov_b32_e32 v87, v4
	v_mov_b32_e32 v88, v4
	v_mov_b32_e32 v89, v4
	v_mov_b32_e32 v90, v4
	v_mov_b32_e32 v91, v4
	v_mov_b32_e32 v100, v4
	v_mov_b32_e32 v101, v4
	v_mov_b32_e32 v102, v4
	v_mov_b32_e32 v103, v4
	v_mov_b32_e32 v104, v4
	v_mov_b32_e32 v105, v4
	v_mov_b32_e32 v106, v4
	v_mov_b32_e32 v107, v4
	v_mov_b32_e32 v116, v4
	v_mov_b32_e32 v117, v4
	v_mov_b32_e32 v118, v4
	v_mov_b32_e32 v119, v4
	v_mov_b32_e32 v120, v4
	v_mov_b32_e32 v121, v4
	v_mov_b32_e32 v122, v4
	v_mov_b32_e32 v123, v4
	v_mov_b32_e32 v76, v4
	v_mov_b32_e32 v77, v4
	v_mov_b32_e32 v78, v4
	v_mov_b32_e32 v79, v4
	v_mov_b32_e32 v80, v4
	v_mov_b32_e32 v81, v4
	v_mov_b32_e32 v82, v4
	v_mov_b32_e32 v83, v4
	v_mov_b32_e32 v92, v4
	v_mov_b32_e32 v93, v4
	v_mov_b32_e32 v94, v4
	v_mov_b32_e32 v95, v4
	v_mov_b32_e32 v96, v4
	v_mov_b32_e32 v97, v4
	v_mov_b32_e32 v98, v4
	v_mov_b32_e32 v99, v4
	v_mov_b32_e32 v108, v4
	v_mov_b32_e32 v109, v4
	v_mov_b32_e32 v110, v4
	v_mov_b32_e32 v111, v4
	v_mov_b32_e32 v112, v4
	v_mov_b32_e32 v113, v4
	v_mov_b32_e32 v114, v4
	v_mov_b32_e32 v115, v4
	v_mov_b32_e32 v124, v4
	v_mov_b32_e32 v125, v4
	v_mov_b32_e32 v126, v4
	v_mov_b32_e32 v127, v4
	v_mov_b32_e32 v128, v4
	v_mov_b32_e32 v129, v4
	v_mov_b32_e32 v130, v4
	v_mov_b32_e32 v131, v4
	s_branch .Lmid_790

.Lmid_790:
	s_waitcnt vmcnt(8)
	s_waitcnt lgkmcnt(0)
	s_setprio 1
	s_barrier
	v_mfma_f32_16x16x32_bf16 v[128:131], v[132:135], v[164:167], v[128:131]
	v_mfma_f32_16x16x32_bf16 v[124:127], v[140:143], v[164:167], v[124:127]
	v_mfma_f32_16x16x32_bf16 v[112:115], v[132:135], v[192:195], v[112:115]
	v_mfma_f32_16x16x32_bf16 v[108:111], v[140:143], v[192:195], v[108:111]
	v_mfma_f32_16x16x32_bf16 v[96:99], v[132:135], v[200:203], v[96:99]
	v_mfma_f32_16x16x32_bf16 v[92:95], v[140:143], v[200:203], v[92:95]
	v_mfma_f32_16x16x32_bf16 v[80:83], v[132:135], v[208:211], v[80:83]
	v_mfma_f32_16x16x32_bf16 v[76:79], v[140:143], v[208:211], v[76:79]
	v_mfma_f32_16x16x32_bf16 v[128:131], v[136:139], v[188:191], v[128:131]
	v_mfma_f32_16x16x32_bf16 v[124:127], v[144:147], v[188:191], v[124:127]
	v_mfma_f32_16x16x32_bf16 v[112:115], v[136:139], v[196:199], v[112:115]
	v_mfma_f32_16x16x32_bf16 v[108:111], v[144:147], v[196:199], v[108:111]
	v_mfma_f32_16x16x32_bf16 v[96:99], v[136:139], v[204:207], v[96:99]
	v_mfma_f32_16x16x32_bf16 v[92:95], v[144:147], v[204:207], v[92:95]
	v_mfma_f32_16x16x32_bf16 v[80:83], v[136:139], v[212:215], v[80:83]
	v_mfma_f32_16x16x32_bf16 v[76:79], v[144:147], v[212:215], v[76:79]
	v_mfma_f32_16x16x32_bf16 v[120:123], v[148:151], v[164:167], v[120:123]
	v_mfma_f32_16x16x32_bf16 v[116:119], v[156:159], v[164:167], v[116:119]
	v_mfma_f32_16x16x32_bf16 v[104:107], v[148:151], v[192:195], v[104:107]
	v_mfma_f32_16x16x32_bf16 v[100:103], v[156:159], v[192:195], v[100:103]
	v_mfma_f32_16x16x32_bf16 v[88:91], v[148:151], v[200:203], v[88:91]
	v_mfma_f32_16x16x32_bf16 v[84:87], v[156:159], v[200:203], v[84:87]
	v_mfma_f32_16x16x32_bf16 v[72:75], v[148:151], v[208:211], v[72:75]
	v_mfma_f32_16x16x32_bf16 v[68:71], v[156:159], v[208:211], v[68:71]
	v_mfma_f32_16x16x32_bf16 v[120:123], v[152:155], v[188:191], v[120:123]
	v_mfma_f32_16x16x32_bf16 v[116:119], v[160:163], v[188:191], v[116:119]
	v_mfma_f32_16x16x32_bf16 v[104:107], v[152:155], v[196:199], v[104:107]
	v_mfma_f32_16x16x32_bf16 v[100:103], v[160:163], v[196:199], v[100:103]
	v_mfma_f32_16x16x32_bf16 v[88:91], v[152:155], v[204:207], v[88:91]
	v_mfma_f32_16x16x32_bf16 v[84:87], v[160:163], v[204:207], v[84:87]
	v_mfma_f32_16x16x32_bf16 v[72:75], v[152:155], v[212:215], v[72:75]
	v_mfma_f32_16x16x32_bf16 v[68:71], v[160:163], v[212:215], v[68:71]
	s_barrier
	s_setprio 0
	s_add_i32 s16, s17, s74
	v_lshl_add_u64 v[174:175], s[28:29], 0, v[2:3]
	s_mov_b32 m0, s16
	ds_read_b128 v[164:167], v246 offset:16384
	ds_read_b128 v[188:191], v246 offset:17408
	ds_read_b128 v[192:195], v246 offset:18432
	ds_read_b128 v[196:199], v246 offset:19456
	ds_read_b128 v[200:203], v246 offset:20480
	ds_read_b128 v[204:207], v246 offset:21504
	ds_read_b128 v[208:211], v246 offset:22528
	ds_read_b128 v[212:215], v246 offset:23552
	global_load_lds_dwordx4 v[174:175], off
	s_add_i32 m0, s16, 0x2000
	s_add_u32 s16, s28, 0x20000
	v_lshl_add_u64 v[176:177], s[28:29], 0, v[168:169]
	s_addc_u32 s17, s29, 0
	s_add_i32 s11, s11, s74
	global_load_lds_dwordx4 v[176:177], off
	v_lshl_add_u64 v[178:179], s[16:17], 0, v[2:3]
	s_mov_b32 m0, s11
	v_lshl_add_u64 v[180:181], s[72:73], 0, v[170:171]
	global_load_lds_dwordx4 v[178:179], off
	v_lshl_add_u64 v[178:179], s[16:17], 0, v[168:169]
	s_add_i32 m0, s11, 0x2000
	s_nop 0
	global_load_lds_dwordx4 v[178:179], off
	v_lshl_add_u64 v[178:179], s[72:73], 0, v[172:173]
	s_mov_b32 m0, s77
	s_nop 0
	global_load_lds_dwordx4 v[178:179], off
	s_mov_b32 m0, s78
	s_nop 0
	global_load_lds_dwordx4 v[180:181], off
	s_waitcnt vmcnt(8)
	s_waitcnt lgkmcnt(0)
	s_setprio 1
	s_barrier
	v_mfma_f32_16x16x32_bf16 v[64:67], v[132:135], v[164:167], v[64:67]
	v_mfma_f32_16x16x32_bf16 v[60:63], v[140:143], v[164:167], v[60:63]
	v_mfma_f32_16x16x32_bf16 v[48:51], v[132:135], v[192:195], v[48:51]
	v_mfma_f32_16x16x32_bf16 v[44:47], v[140:143], v[192:195], v[44:47]
	v_mfma_f32_16x16x32_bf16 v[32:35], v[132:135], v[200:203], v[32:35]
	v_mfma_f32_16x16x32_bf16 v[28:31], v[140:143], v[200:203], v[28:31]
	v_mfma_f32_16x16x32_bf16 v[16:19], v[132:135], v[208:211], v[16:19]
	v_mfma_f32_16x16x32_bf16 v[12:15], v[140:143], v[208:211], v[12:15]
	v_mfma_f32_16x16x32_bf16 v[64:67], v[136:139], v[188:191], v[64:67]
	v_mfma_f32_16x16x32_bf16 v[60:63], v[144:147], v[188:191], v[60:63]
	v_mfma_f32_16x16x32_bf16 v[48:51], v[136:139], v[196:199], v[48:51]
	v_mfma_f32_16x16x32_bf16 v[44:47], v[144:147], v[196:199], v[44:47]
	v_mfma_f32_16x16x32_bf16 v[32:35], v[136:139], v[204:207], v[32:35]
	v_mfma_f32_16x16x32_bf16 v[28:31], v[144:147], v[204:207], v[28:31]
	v_mfma_f32_16x16x32_bf16 v[16:19], v[136:139], v[212:215], v[16:19]
	v_mfma_f32_16x16x32_bf16 v[12:15], v[144:147], v[212:215], v[12:15]
	v_mfma_f32_16x16x32_bf16 v[56:59], v[148:151], v[164:167], v[56:59]
	v_mfma_f32_16x16x32_bf16 v[52:55], v[156:159], v[164:167], v[52:55]
	v_mfma_f32_16x16x32_bf16 v[40:43], v[148:151], v[192:195], v[40:43]
	v_mfma_f32_16x16x32_bf16 v[36:39], v[156:159], v[192:195], v[36:39]
	v_mfma_f32_16x16x32_bf16 v[24:27], v[148:151], v[200:203], v[24:27]
	v_mfma_f32_16x16x32_bf16 v[20:23], v[156:159], v[200:203], v[20:23]
	v_mfma_f32_16x16x32_bf16 v[8:11], v[148:151], v[208:211], v[8:11]
	v_mfma_f32_16x16x32_bf16 v[4:7], v[156:159], v[208:211], v[4:7]
	v_mfma_f32_16x16x32_bf16 v[56:59], v[152:155], v[188:191], v[56:59]
	v_mfma_f32_16x16x32_bf16 v[52:55], v[160:163], v[188:191], v[52:55]
	v_mfma_f32_16x16x32_bf16 v[40:43], v[152:155], v[196:199], v[40:43]
	v_mfma_f32_16x16x32_bf16 v[36:39], v[160:163], v[196:199], v[36:39]
	v_mfma_f32_16x16x32_bf16 v[24:27], v[152:155], v[204:207], v[24:27]
	v_mfma_f32_16x16x32_bf16 v[20:23], v[160:163], v[204:207], v[20:23]
	v_mfma_f32_16x16x32_bf16 v[8:11], v[152:155], v[212:215], v[8:11]
	v_mfma_f32_16x16x32_bf16 v[4:7], v[160:163], v[212:215], v[4:7]
	s_barrier
	s_setprio 0
	s_add_i32 s11, 0, 0x18000
	s_add_i32 s94, 0, 0x1c000
	v_add_u32_e32 v144, s11, v244
	v_add_u32_e32 v160, s94, v244
	ds_read_b128 v[132:135], v144
	ds_read_b128 v[136:139], v144 offset:1024
	ds_read_b128 v[140:143], v144 offset:2048
	ds_read_b128 v[144:147], v144 offset:3072
	ds_read_b128 v[148:151], v160
	ds_read_b128 v[152:155], v160 offset:1024
	ds_read_b128 v[156:159], v160 offset:2048
	ds_read_b128 v[160:163], v160 offset:3072
	s_add_u32 s16, s72, 0x80000
	s_addc_u32 s17, s73, 0
	s_mov_b32 m0, s95
	v_lshl_add_u64 v[182:183], s[16:17], 0, v[172:173]
	ds_read_b128 v[164:167], v246 offset:32768
	ds_read_b128 v[188:191], v246 offset:33792
	ds_read_b128 v[192:195], v246 offset:34816
	ds_read_b128 v[196:199], v246 offset:35840
	ds_read_b128 v[200:203], v246 offset:36864
	ds_read_b128 v[204:207], v246 offset:37888
	ds_read_b128 v[208:211], v246 offset:38912
	ds_read_b128 v[212:215], v246 offset:39936
	global_load_lds_dwordx4 v[182:183], off
	v_lshl_add_u64 v[182:183], s[16:17], 0, v[170:171]
	s_mov_b32 m0, s68
	s_nop 0
	global_load_lds_dwordx4 v[182:183], off
	s_waitcnt vmcnt(8)
	s_waitcnt lgkmcnt(0)
	s_setprio 1
	s_barrier
	v_mfma_f32_16x16x32_bf16 v[128:131], v[132:135], v[164:167], v[128:131]
	v_mfma_f32_16x16x32_bf16 v[124:127], v[140:143], v[164:167], v[124:127]
	v_mfma_f32_16x16x32_bf16 v[112:115], v[132:135], v[192:195], v[112:115]
	v_mfma_f32_16x16x32_bf16 v[108:111], v[140:143], v[192:195], v[108:111]
	v_mfma_f32_16x16x32_bf16 v[96:99], v[132:135], v[200:203], v[96:99]
	v_mfma_f32_16x16x32_bf16 v[92:95], v[140:143], v[200:203], v[92:95]
	v_mfma_f32_16x16x32_bf16 v[80:83], v[132:135], v[208:211], v[80:83]
	v_mfma_f32_16x16x32_bf16 v[76:79], v[140:143], v[208:211], v[76:79]
	v_mfma_f32_16x16x32_bf16 v[128:131], v[136:139], v[188:191], v[128:131]
	v_mfma_f32_16x16x32_bf16 v[124:127], v[144:147], v[188:191], v[124:127]
	v_mfma_f32_16x16x32_bf16 v[112:115], v[136:139], v[196:199], v[112:115]
	v_mfma_f32_16x16x32_bf16 v[108:111], v[144:147], v[196:199], v[108:111]
	v_mfma_f32_16x16x32_bf16 v[96:99], v[136:139], v[204:207], v[96:99]
	v_mfma_f32_16x16x32_bf16 v[92:95], v[144:147], v[204:207], v[92:95]
	v_mfma_f32_16x16x32_bf16 v[80:83], v[136:139], v[212:215], v[80:83]
	v_mfma_f32_16x16x32_bf16 v[76:79], v[144:147], v[212:215], v[76:79]
	v_mfma_f32_16x16x32_bf16 v[120:123], v[148:151], v[164:167], v[120:123]
	v_mfma_f32_16x16x32_bf16 v[116:119], v[156:159], v[164:167], v[116:119]
	v_mfma_f32_16x16x32_bf16 v[104:107], v[148:151], v[192:195], v[104:107]
	v_mfma_f32_16x16x32_bf16 v[100:103], v[156:159], v[192:195], v[100:103]
	v_mfma_f32_16x16x32_bf16 v[88:91], v[148:151], v[200:203], v[88:91]
	v_mfma_f32_16x16x32_bf16 v[84:87], v[156:159], v[200:203], v[84:87]
	v_mfma_f32_16x16x32_bf16 v[72:75], v[148:151], v[208:211], v[72:75]
	v_mfma_f32_16x16x32_bf16 v[68:71], v[156:159], v[208:211], v[68:71]
	v_mfma_f32_16x16x32_bf16 v[120:123], v[152:155], v[188:191], v[120:123]
	v_mfma_f32_16x16x32_bf16 v[116:119], v[160:163], v[188:191], v[116:119]
	v_mfma_f32_16x16x32_bf16 v[104:107], v[152:155], v[196:199], v[104:107]
	v_mfma_f32_16x16x32_bf16 v[100:103], v[160:163], v[196:199], v[100:103]
	v_mfma_f32_16x16x32_bf16 v[88:91], v[152:155], v[204:207], v[88:91]
	v_mfma_f32_16x16x32_bf16 v[84:87], v[160:163], v[204:207], v[84:87]
	v_mfma_f32_16x16x32_bf16 v[72:75], v[152:155], v[212:215], v[72:75]
	v_mfma_f32_16x16x32_bf16 v[68:71], v[160:163], v[212:215], v[68:71]
	s_barrier
	s_setprio 0
	s_add_i32 s11, s11, s74
	v_lshl_add_u64 v[174:175], v[174:175], 0, s[24:25]
	s_mov_b32 m0, s11
	ds_read_b128 v[164:167], v246 offset:49152
	ds_read_b128 v[188:191], v246 offset:50176
	ds_read_b128 v[192:195], v246 offset:51200
	ds_read_b128 v[196:199], v246 offset:52224
	ds_read_b128 v[200:203], v246 offset:53248
	ds_read_b128 v[204:207], v246 offset:54272
	ds_read_b128 v[208:211], v246 offset:55296
	ds_read_b128 v[212:215], v246 offset:56320
	global_load_lds_dwordx4 v[174:175], off
	s_add_i32 m0, s11, 0x2000
	s_add_u32 s16, s28, 0x20080
	v_lshl_add_u64 v[174:175], v[176:177], 0, s[24:25]
	s_addc_u32 s17, s29, 0
	s_add_i32 s11, s94, s74
	global_load_lds_dwordx4 v[174:175], off
	v_lshl_add_u64 v[174:175], s[16:17], 0, v[2:3]
	s_mov_b32 m0, s11
	s_nop 0
	global_load_lds_dwordx4 v[174:175], off
	v_lshl_add_u64 v[174:175], s[16:17], 0, v[168:169]
	s_add_i32 m0, s11, 0x2000
	s_nop 0
	global_load_lds_dwordx4 v[174:175], off
	v_lshl_add_u64 v[174:175], v[178:179], 0, s[24:25]
	s_mov_b32 m0, s96
	s_nop 0
	global_load_lds_dwordx4 v[174:175], off
	v_lshl_add_u64 v[174:175], v[180:181], 0, s[24:25]
	s_mov_b32 m0, s3
	s_nop 0
	global_load_lds_dwordx4 v[174:175], off
	s_waitcnt vmcnt(8)
	s_waitcnt lgkmcnt(0)
	s_setprio 1
	s_barrier
	v_mfma_f32_16x16x32_bf16 v[64:67], v[132:135], v[164:167], v[64:67]
	v_mfma_f32_16x16x32_bf16 v[60:63], v[140:143], v[164:167], v[60:63]
	v_mfma_f32_16x16x32_bf16 v[48:51], v[132:135], v[192:195], v[48:51]
	v_mfma_f32_16x16x32_bf16 v[44:47], v[140:143], v[192:195], v[44:47]
	v_mfma_f32_16x16x32_bf16 v[32:35], v[132:135], v[200:203], v[32:35]
	v_mfma_f32_16x16x32_bf16 v[28:31], v[140:143], v[200:203], v[28:31]
	v_mfma_f32_16x16x32_bf16 v[16:19], v[132:135], v[208:211], v[16:19]
	v_mfma_f32_16x16x32_bf16 v[12:15], v[140:143], v[208:211], v[12:15]
	v_mfma_f32_16x16x32_bf16 v[64:67], v[136:139], v[188:191], v[64:67]
	v_mfma_f32_16x16x32_bf16 v[60:63], v[144:147], v[188:191], v[60:63]
	v_mfma_f32_16x16x32_bf16 v[48:51], v[136:139], v[196:199], v[48:51]
	v_mfma_f32_16x16x32_bf16 v[44:47], v[144:147], v[196:199], v[44:47]
	v_mfma_f32_16x16x32_bf16 v[32:35], v[136:139], v[204:207], v[32:35]
	v_mfma_f32_16x16x32_bf16 v[28:31], v[144:147], v[204:207], v[28:31]
	v_mfma_f32_16x16x32_bf16 v[16:19], v[136:139], v[212:215], v[16:19]
	v_mfma_f32_16x16x32_bf16 v[12:15], v[144:147], v[212:215], v[12:15]
	v_mfma_f32_16x16x32_bf16 v[56:59], v[148:151], v[164:167], v[56:59]
	v_mfma_f32_16x16x32_bf16 v[52:55], v[156:159], v[164:167], v[52:55]
	v_mfma_f32_16x16x32_bf16 v[40:43], v[148:151], v[192:195], v[40:43]
	v_mfma_f32_16x16x32_bf16 v[36:39], v[156:159], v[192:195], v[36:39]
	v_mfma_f32_16x16x32_bf16 v[24:27], v[148:151], v[200:203], v[24:27]
	v_mfma_f32_16x16x32_bf16 v[20:23], v[156:159], v[200:203], v[20:23]
	v_mfma_f32_16x16x32_bf16 v[8:11], v[148:151], v[208:211], v[8:11]
	v_mfma_f32_16x16x32_bf16 v[4:7], v[156:159], v[208:211], v[4:7]
	v_mfma_f32_16x16x32_bf16 v[56:59], v[152:155], v[188:191], v[56:59]
	v_mfma_f32_16x16x32_bf16 v[52:55], v[160:163], v[188:191], v[52:55]
	v_mfma_f32_16x16x32_bf16 v[40:43], v[152:155], v[196:199], v[40:43]
	v_mfma_f32_16x16x32_bf16 v[36:39], v[160:163], v[196:199], v[36:39]
	v_mfma_f32_16x16x32_bf16 v[24:27], v[152:155], v[204:207], v[24:27]
	v_mfma_f32_16x16x32_bf16 v[20:23], v[160:163], v[204:207], v[20:23]
	v_mfma_f32_16x16x32_bf16 v[8:11], v[152:155], v[212:215], v[8:11]
	v_mfma_f32_16x16x32_bf16 v[4:7], v[160:163], v[212:215], v[4:7]
	s_barrier
	s_setprio 0
	s_add_i32 s10, s10, 2
	s_add_u32 vcc_lo, vcc_lo, 0x100
	s_addc_u32 vcc_hi, vcc_hi, 0
	s_add_u32 s48, s48, 0x100
	s_addc_u32 s49, s49, 0
	s_cmp_gt_u32 s10, 29
	s_cbranch_scc0 .LBB0_790
	v_readlane_b32 s10, v252, 2
	v_readlane_b32 s11, v252, 3

.LBB0_869:
	s_ashr_i32 s37, s36, 31
	s_lshl_b64 s[16:17], s[36:37], 20
	s_add_u32 s40, s0, s16
	s_addc_u32 s41, s1, s17
	s_and_b64 s[16:17], s[38:39], exec
	s_cselect_b32 s37, s41, s45
	s_cselect_b32 s88, s40, s44
	s_ashr_i32 s27, s26, 31
	s_lshl_b64 s[16:17], s[26:27], 20
	s_add_u32 s42, s3, s16
	s_addc_u32 s43, s31, s17
	s_and_b64 s[16:17], s[38:39], exec
	s_cselect_b32 s27, s43, s29
	s_cselect_b32 s89, s42, s28
	s_add_u32 s44, s44, 0x80080
	s_addc_u32 s45, s45, 0
	s_add_u32 s91, s28, 0x100
	s_addc_u32 s96, s29, 0
	s_mov_b32 vcc_lo, -2
	s_waitcnt lgkmcnt(0)
	s_waitcnt vmcnt(0)
	s_add_u32 s16, s44, 0xfff80080
	s_addc_u32 s17, s45, -1
	s_add_i32 s94, 0, 0x10000
	s_cmp_eq_u32 vcc_lo, 28
	s_cselect_b32 s47, s37, s17
	s_cselect_b32 s46, s88, s16
	s_cselect_b32 s29, s27, s96
	s_cselect_b32 s28, s89, s91
	s_add_i32 s95, 0, 0x14000
	v_add_u32_e32 v144, s94, v227
	v_add_u32_e32 v170, s95, v227
	ds_read_b128 v[132:135], v144
	ds_read_b128 v[136:139], v144 offset:1024
	ds_read_b128 v[140:143], v144 offset:2048
	ds_read_b128 v[144:147], v144 offset:3072
	ds_read_b128 v[148:151], v170
	ds_read_b128 v[152:155], v170 offset:1024
	ds_read_b128 v[166:169], v170 offset:2048
	ds_read_b128 v[170:173], v170 offset:3072
	v_lshl_add_u64 v[174:175], s[44:45], 0, v[162:163]
	s_add_i32 m0, s48, 0xc000
	ds_read_b128 v[184:187], v229
	ds_read_b128 v[188:191], v229 offset:1024
	ds_read_b128 v[192:195], v229 offset:2048
	ds_read_b128 v[196:199], v229 offset:3072
	ds_read_b128 v[200:203], v229 offset:4096
	ds_read_b128 v[204:207], v229 offset:5120
	ds_read_b128 v[208:211], v229 offset:6144
	ds_read_b128 v[212:215], v229 offset:7168
	global_load_lds_dwordx4 v[174:175], off
	v_lshl_add_u64 v[174:175], s[44:45], 0, v[164:165]
	s_add_i32 m0, s48, 0xe000
	s_nop 0
	global_load_lds_dwordx4 v[174:175], off
	v_mov_b32_e32 v4, 0
	v_mov_b32_e32 v5, v4
	v_mov_b32_e32 v6, v4
	v_mov_b32_e32 v7, v4
	v_mov_b32_e32 v8, v4
	v_mov_b32_e32 v9, v4
	v_mov_b32_e32 v10, v4
	v_mov_b32_e32 v11, v4
	v_mov_b32_e32 v20, v4
	v_mov_b32_e32 v21, v4
	v_mov_b32_e32 v22, v4
	v_mov_b32_e32 v23, v4
	v_mov_b32_e32 v24, v4
	v_mov_b32_e32 v25, v4
	v_mov_b32_e32 v26, v4
	v_mov_b32_e32 v27, v4
	v_mov_b32_e32 v36, v4
	v_mov_b32_e32 v37, v4
	v_mov_b32_e32 v38, v4
	v_mov_b32_e32 v39, v4
	v_mov_b32_e32 v40, v4
	v_mov_b32_e32 v41, v4
	v_mov_b32_e32 v42, v4
	v_mov_b32_e32 v43, v4
	v_mov_b32_e32 v52, v4
	v_mov_b32_e32 v53, v4
	v_mov_b32_e32 v54, v4
	v_mov_b32_e32 v55, v4
	v_mov_b32_e32 v56, v4
	v_mov_b32_e32 v57, v4
	v_mov_b32_e32 v58, v4
	v_mov_b32_e32 v59, v4
	v_mov_b32_e32 v12, v4
	v_mov_b32_e32 v13, v4
	v_mov_b32_e32 v14, v4
	v_mov_b32_e32 v15, v4
	v_mov_b32_e32 v16, v4
	v_mov_b32_e32 v17, v4
	v_mov_b32_e32 v18, v4
	v_mov_b32_e32 v19, v4
	v_mov_b32_e32 v28, v4
	v_mov_b32_e32 v29, v4
	v_mov_b32_e32 v30, v4
	v_mov_b32_e32 v31, v4
	v_mov_b32_e32 v32, v4
	v_mov_b32_e32 v33, v4
	v_mov_b32_e32 v34, v4
	v_mov_b32_e32 v35, v4
	v_mov_b32_e32 v44, v4
	v_mov_b32_e32 v45, v4
	v_mov_b32_e32 v46, v4
	v_mov_b32_e32 v47, v4
	v_mov_b32_e32 v48, v4
	v_mov_b32_e32 v49, v4
	v_mov_b32_e32 v50, v4
	v_mov_b32_e32 v51, v4
	v_mov_b32_e32 v60, v4
	v_mov_b32_e32 v61, v4
	v_mov_b32_e32 v62, v4
	v_mov_b32_e32 v63, v4
	v_mov_b32_e32 v64, v4
	v_mov_b32_e32 v65, v4
	v_mov_b32_e32 v66, v4
	v_mov_b32_e32 v67, v4
	v_mov_b32_e32 v68, v4
	v_mov_b32_e32 v69, v4
	v_mov_b32_e32 v70, v4
	v_mov_b32_e32 v71, v4
	v_mov_b32_e32 v72, v4
	v_mov_b32_e32 v73, v4
	v_mov_b32_e32 v74, v4
	v_mov_b32_e32 v75, v4
	v_mov_b32_e32 v84, v4
	v_mov_b32_e32 v85, v4
	v_mov_b32_e32 v86, v4
	v_mov_b32_e32 v87, v4
	v_mov_b32_e32 v88, v4
	v_mov_b32_e32 v89, v4
	v_mov_b32_e32 v90, v4
	v_mov_b32_e32 v91, v4
	v_mov_b32_e32 v100, v4
	v_mov_b32_e32 v101, v4
	v_mov_b32_e32 v102, v4
	v_mov_b32_e32 v103, v4
	v_mov_b32_e32 v104, v4
	v_mov_b32_e32 v105, v4
	v_mov_b32_e32 v106, v4
	v_mov_b32_e32 v107, v4
	v_mov_b32_e32 v116, v4
	v_mov_b32_e32 v117, v4
	v_mov_b32_e32 v118, v4
	v_mov_b32_e32 v119, v4
	v_mov_b32_e32 v120, v4
	v_mov_b32_e32 v121, v4
	v_mov_b32_e32 v122, v4
	v_mov_b32_e32 v123, v4
	v_mov_b32_e32 v76, v4
	v_mov_b32_e32 v77, v4
	v_mov_b32_e32 v78, v4
	v_mov_b32_e32 v79, v4
	v_mov_b32_e32 v80, v4
	v_mov_b32_e32 v81, v4
	v_mov_b32_e32 v82, v4
	v_mov_b32_e32 v83, v4
	v_mov_b32_e32 v92, v4
	v_mov_b32_e32 v93, v4
	v_mov_b32_e32 v94, v4
	v_mov_b32_e32 v95, v4
	v_mov_b32_e32 v96, v4
	v_mov_b32_e32 v97, v4
	v_mov_b32_e32 v98, v4
	v_mov_b32_e32 v99, v4
	v_mov_b32_e32 v108, v4
	v_mov_b32_e32 v109, v4
	v_mov_b32_e32 v110, v4
	v_mov_b32_e32 v111, v4
	v_mov_b32_e32 v112, v4
	v_mov_b32_e32 v113, v4
	v_mov_b32_e32 v114, v4
	v_mov_b32_e32 v115, v4
	v_mov_b32_e32 v124, v4
	v_mov_b32_e32 v125, v4
	v_mov_b32_e32 v126, v4
	v_mov_b32_e32 v127, v4
	v_mov_b32_e32 v128, v4
	v_mov_b32_e32 v129, v4
	v_mov_b32_e32 v130, v4
	v_mov_b32_e32 v131, v4
	s_branch .Lmid_870

.Lmid_870:
	s_waitcnt vmcnt(8)
	s_waitcnt lgkmcnt(0)
	s_setprio 1
	s_barrier
	v_mfma_f32_16x16x32_bf16 v[128:131], v[132:135], v[184:187], v[128:131]
	v_mfma_f32_16x16x32_bf16 v[124:127], v[140:143], v[184:187], v[124:127]
	v_mfma_f32_16x16x32_bf16 v[112:115], v[132:135], v[192:195], v[112:115]
	v_mfma_f32_16x16x32_bf16 v[108:111], v[140:143], v[192:195], v[108:111]
	v_mfma_f32_16x16x32_bf16 v[96:99], v[132:135], v[200:203], v[96:99]
	v_mfma_f32_16x16x32_bf16 v[92:95], v[140:143], v[200:203], v[92:95]
	v_mfma_f32_16x16x32_bf16 v[80:83], v[132:135], v[208:211], v[80:83]
	v_mfma_f32_16x16x32_bf16 v[76:79], v[140:143], v[208:211], v[76:79]
	v_mfma_f32_16x16x32_bf16 v[128:131], v[136:139], v[188:191], v[128:131]
	v_mfma_f32_16x16x32_bf16 v[124:127], v[144:147], v[188:191], v[124:127]
	v_mfma_f32_16x16x32_bf16 v[112:115], v[136:139], v[196:199], v[112:115]
	v_mfma_f32_16x16x32_bf16 v[108:111], v[144:147], v[196:199], v[108:111]
	v_mfma_f32_16x16x32_bf16 v[96:99], v[136:139], v[204:207], v[96:99]
	v_mfma_f32_16x16x32_bf16 v[92:95], v[144:147], v[204:207], v[92:95]
	v_mfma_f32_16x16x32_bf16 v[80:83], v[136:139], v[212:215], v[80:83]
	v_mfma_f32_16x16x32_bf16 v[76:79], v[144:147], v[212:215], v[76:79]
	v_mfma_f32_16x16x32_bf16 v[120:123], v[148:151], v[184:187], v[120:123]
	v_mfma_f32_16x16x32_bf16 v[116:119], v[166:169], v[184:187], v[116:119]
	v_mfma_f32_16x16x32_bf16 v[104:107], v[148:151], v[192:195], v[104:107]
	v_mfma_f32_16x16x32_bf16 v[100:103], v[166:169], v[192:195], v[100:103]
	v_mfma_f32_16x16x32_bf16 v[88:91], v[148:151], v[200:203], v[88:91]
	v_mfma_f32_16x16x32_bf16 v[84:87], v[166:169], v[200:203], v[84:87]
	v_mfma_f32_16x16x32_bf16 v[72:75], v[148:151], v[208:211], v[72:75]
	v_mfma_f32_16x16x32_bf16 v[68:71], v[166:169], v[208:211], v[68:71]
	v_mfma_f32_16x16x32_bf16 v[120:123], v[152:155], v[188:191], v[120:123]
	v_mfma_f32_16x16x32_bf16 v[116:119], v[170:173], v[188:191], v[116:119]
	v_mfma_f32_16x16x32_bf16 v[104:107], v[152:155], v[196:199], v[104:107]
	v_mfma_f32_16x16x32_bf16 v[100:103], v[170:173], v[196:199], v[100:103]
	v_mfma_f32_16x16x32_bf16 v[88:91], v[152:155], v[204:207], v[88:91]
	v_mfma_f32_16x16x32_bf16 v[84:87], v[170:173], v[204:207], v[84:87]
	v_mfma_f32_16x16x32_bf16 v[72:75], v[152:155], v[212:215], v[72:75]
	v_mfma_f32_16x16x32_bf16 v[68:71], v[170:173], v[212:215], v[68:71]
	s_barrier
	s_setprio 0
	s_add_i32 s16, s94, s33
	v_lshl_add_u64 v[174:175], s[28:29], 0, v[2:3]
	s_mov_b32 m0, s16
	ds_read_b128 v[184:187], v229 offset:16384
	ds_read_b128 v[188:191], v229 offset:17408
	ds_read_b128 v[192:195], v229 offset:18432
	ds_read_b128 v[196:199], v229 offset:19456
	ds_read_b128 v[200:203], v229 offset:20480
	ds_read_b128 v[204:207], v229 offset:21504
	ds_read_b128 v[208:211], v229 offset:22528
	ds_read_b128 v[212:215], v229 offset:23552
	global_load_lds_dwordx4 v[174:175], off
	s_add_i32 m0, s16, 0x2000
	s_add_u32 s16, s28, 0x80000
	v_lshl_add_u64 v[176:177], s[28:29], 0, v[156:157]
	s_addc_u32 s17, s29, 0
	s_add_i32 s94, s95, s33
	global_load_lds_dwordx4 v[176:177], off
	v_lshl_add_u64 v[178:179], s[16:17], 0, v[2:3]
	s_mov_b32 m0, s94
	v_lshl_add_u64 v[180:181], s[46:47], 0, v[158:159]
	global_load_lds_dwordx4 v[178:179], off
	v_lshl_add_u64 v[178:179], s[16:17], 0, v[156:157]
	s_add_i32 m0, s94, 0x2000
	s_nop 0
	global_load_lds_dwordx4 v[178:179], off
	v_lshl_add_u64 v[178:179], s[46:47], 0, v[160:161]
	s_mov_b32 m0, s48
	s_nop 0
	global_load_lds_dwordx4 v[178:179], off
	s_mov_b32 m0, s49
	s_nop 0
	global_load_lds_dwordx4 v[180:181], off
	s_waitcnt vmcnt(8)
	s_waitcnt lgkmcnt(0)
	s_setprio 1
	s_barrier
	v_mfma_f32_16x16x32_bf16 v[64:67], v[132:135], v[184:187], v[64:67]
	v_mfma_f32_16x16x32_bf16 v[60:63], v[140:143], v[184:187], v[60:63]
	v_mfma_f32_16x16x32_bf16 v[48:51], v[132:135], v[192:195], v[48:51]
	v_mfma_f32_16x16x32_bf16 v[44:47], v[140:143], v[192:195], v[44:47]
	v_mfma_f32_16x16x32_bf16 v[32:35], v[132:135], v[200:203], v[32:35]
	v_mfma_f32_16x16x32_bf16 v[28:31], v[140:143], v[200:203], v[28:31]
	v_mfma_f32_16x16x32_bf16 v[16:19], v[132:135], v[208:211], v[16:19]
	v_mfma_f32_16x16x32_bf16 v[12:15], v[140:143], v[208:211], v[12:15]
	v_mfma_f32_16x16x32_bf16 v[64:67], v[136:139], v[188:191], v[64:67]
	v_mfma_f32_16x16x32_bf16 v[60:63], v[144:147], v[188:191], v[60:63]
	v_mfma_f32_16x16x32_bf16 v[48:51], v[136:139], v[196:199], v[48:51]
	v_mfma_f32_16x16x32_bf16 v[44:47], v[144:147], v[196:199], v[44:47]
	v_mfma_f32_16x16x32_bf16 v[32:35], v[136:139], v[204:207], v[32:35]
	v_mfma_f32_16x16x32_bf16 v[28:31], v[144:147], v[204:207], v[28:31]
	v_mfma_f32_16x16x32_bf16 v[16:19], v[136:139], v[212:215], v[16:19]
	v_mfma_f32_16x16x32_bf16 v[12:15], v[144:147], v[212:215], v[12:15]
	v_mfma_f32_16x16x32_bf16 v[56:59], v[148:151], v[184:187], v[56:59]
	v_mfma_f32_16x16x32_bf16 v[52:55], v[166:169], v[184:187], v[52:55]
	v_mfma_f32_16x16x32_bf16 v[40:43], v[148:151], v[192:195], v[40:43]
	v_mfma_f32_16x16x32_bf16 v[36:39], v[166:169], v[192:195], v[36:39]
	v_mfma_f32_16x16x32_bf16 v[24:27], v[148:151], v[200:203], v[24:27]
	v_mfma_f32_16x16x32_bf16 v[20:23], v[166:169], v[200:203], v[20:23]
	v_mfma_f32_16x16x32_bf16 v[8:11], v[148:151], v[208:211], v[8:11]
	v_mfma_f32_16x16x32_bf16 v[4:7], v[166:169], v[208:211], v[4:7]
	v_mfma_f32_16x16x32_bf16 v[56:59], v[152:155], v[188:191], v[56:59]
	v_mfma_f32_16x16x32_bf16 v[52:55], v[170:173], v[188:191], v[52:55]
	v_mfma_f32_16x16x32_bf16 v[40:43], v[152:155], v[196:199], v[40:43]
	v_mfma_f32_16x16x32_bf16 v[36:39], v[170:173], v[196:199], v[36:39]
	v_mfma_f32_16x16x32_bf16 v[24:27], v[152:155], v[204:207], v[24:27]
	v_mfma_f32_16x16x32_bf16 v[20:23], v[170:173], v[204:207], v[20:23]
	v_mfma_f32_16x16x32_bf16 v[8:11], v[152:155], v[212:215], v[8:11]
	v_mfma_f32_16x16x32_bf16 v[4:7], v[170:173], v[212:215], v[4:7]
	s_barrier
	s_setprio 0
	s_add_i32 s94, 0, 0x18000
	s_add_i32 s95, 0, 0x1c000
	v_add_u32_e32 v144, s94, v227
	v_add_u32_e32 v170, s95, v227
	ds_read_b128 v[132:135], v144
	ds_read_b128 v[136:139], v144 offset:1024
	ds_read_b128 v[140:143], v144 offset:2048
	ds_read_b128 v[144:147], v144 offset:3072
	ds_read_b128 v[148:151], v170
	ds_read_b128 v[152:155], v170 offset:1024
	ds_read_b128 v[166:169], v170 offset:2048
	ds_read_b128 v[170:173], v170 offset:3072
	s_add_u32 s16, s46, 0x80000
	s_addc_u32 s17, s47, 0
	s_mov_b32 m0, s50
	v_lshl_add_u64 v[182:183], s[16:17], 0, v[160:161]
	ds_read_b128 v[184:187], v229 offset:32768
	ds_read_b128 v[188:191], v229 offset:33792
	ds_read_b128 v[192:195], v229 offset:34816
	ds_read_b128 v[196:199], v229 offset:35840
	ds_read_b128 v[200:203], v229 offset:36864
	ds_read_b128 v[204:207], v229 offset:37888
	ds_read_b128 v[208:211], v229 offset:38912
	ds_read_b128 v[212:215], v229 offset:39936
	global_load_lds_dwordx4 v[182:183], off
	v_lshl_add_u64 v[182:183], s[16:17], 0, v[158:159]
	s_mov_b32 m0, s51
	s_nop 0
	global_load_lds_dwordx4 v[182:183], off
	s_waitcnt vmcnt(8)
	s_waitcnt lgkmcnt(0)
	s_setprio 1
	s_barrier
	v_mfma_f32_16x16x32_bf16 v[128:131], v[132:135], v[184:187], v[128:131]
	v_mfma_f32_16x16x32_bf16 v[124:127], v[140:143], v[184:187], v[124:127]
	v_mfma_f32_16x16x32_bf16 v[112:115], v[132:135], v[192:195], v[112:115]
	v_mfma_f32_16x16x32_bf16 v[108:111], v[140:143], v[192:195], v[108:111]
	v_mfma_f32_16x16x32_bf16 v[96:99], v[132:135], v[200:203], v[96:99]
	v_mfma_f32_16x16x32_bf16 v[92:95], v[140:143], v[200:203], v[92:95]
	v_mfma_f32_16x16x32_bf16 v[80:83], v[132:135], v[208:211], v[80:83]
	v_mfma_f32_16x16x32_bf16 v[76:79], v[140:143], v[208:211], v[76:79]
	v_mfma_f32_16x16x32_bf16 v[128:131], v[136:139], v[188:191], v[128:131]
	v_mfma_f32_16x16x32_bf16 v[124:127], v[144:147], v[188:191], v[124:127]
	v_mfma_f32_16x16x32_bf16 v[112:115], v[136:139], v[196:199], v[112:115]
	v_mfma_f32_16x16x32_bf16 v[108:111], v[144:147], v[196:199], v[108:111]
	v_mfma_f32_16x16x32_bf16 v[96:99], v[136:139], v[204:207], v[96:99]
	v_mfma_f32_16x16x32_bf16 v[92:95], v[144:147], v[204:207], v[92:95]
	v_mfma_f32_16x16x32_bf16 v[80:83], v[136:139], v[212:215], v[80:83]
	v_mfma_f32_16x16x32_bf16 v[76:79], v[144:147], v[212:215], v[76:79]
	v_mfma_f32_16x16x32_bf16 v[120:123], v[148:151], v[184:187], v[120:123]
	v_mfma_f32_16x16x32_bf16 v[116:119], v[166:169], v[184:187], v[116:119]
	v_mfma_f32_16x16x32_bf16 v[104:107], v[148:151], v[192:195], v[104:107]
	v_mfma_f32_16x16x32_bf16 v[100:103], v[166:169], v[192:195], v[100:103]
	v_mfma_f32_16x16x32_bf16 v[88:91], v[148:151], v[200:203], v[88:91]
	v_mfma_f32_16x16x32_bf16 v[84:87], v[166:169], v[200:203], v[84:87]
	v_mfma_f32_16x16x32_bf16 v[72:75], v[148:151], v[208:211], v[72:75]
	v_mfma_f32_16x16x32_bf16 v[68:71], v[166:169], v[208:211], v[68:71]
	v_mfma_f32_16x16x32_bf16 v[120:123], v[152:155], v[188:191], v[120:123]
	v_mfma_f32_16x16x32_bf16 v[116:119], v[170:173], v[188:191], v[116:119]
	v_mfma_f32_16x16x32_bf16 v[104:107], v[152:155], v[196:199], v[104:107]
	v_mfma_f32_16x16x32_bf16 v[100:103], v[170:173], v[196:199], v[100:103]
	v_mfma_f32_16x16x32_bf16 v[88:91], v[152:155], v[204:207], v[88:91]
	v_mfma_f32_16x16x32_bf16 v[84:87], v[170:173], v[204:207], v[84:87]
	v_mfma_f32_16x16x32_bf16 v[72:75], v[152:155], v[212:215], v[72:75]
	v_mfma_f32_16x16x32_bf16 v[68:71], v[170:173], v[212:215], v[68:71]
	s_barrier
	s_setprio 0
	s_add_i32 s16, s94, s33
	v_lshl_add_u64 v[174:175], v[174:175], 0, s[24:25]
	s_mov_b32 m0, s16
	ds_read_b128 v[184:187], v229 offset:49152
	ds_read_b128 v[188:191], v229 offset:50176
	ds_read_b128 v[192:195], v229 offset:51200
	ds_read_b128 v[196:199], v229 offset:52224
	ds_read_b128 v[200:203], v229 offset:53248
	ds_read_b128 v[204:207], v229 offset:54272
	ds_read_b128 v[208:211], v229 offset:55296
	ds_read_b128 v[212:215], v229 offset:56320
	global_load_lds_dwordx4 v[174:175], off
	s_add_i32 m0, s16, 0x2000
	s_add_u32 s16, s28, 0x80080
	v_lshl_add_u64 v[174:175], v[176:177], 0, s[24:25]
	s_addc_u32 s17, s29, 0
	s_add_i32 s28, s95, s33
	global_load_lds_dwordx4 v[174:175], off
	v_lshl_add_u64 v[174:175], s[16:17], 0, v[2:3]
	s_mov_b32 m0, s28
	s_nop 0
	global_load_lds_dwordx4 v[174:175], off
	v_lshl_add_u64 v[174:175], s[16:17], 0, v[156:157]
	s_add_i32 m0, s28, 0x2000
	s_nop 0
	global_load_lds_dwordx4 v[174:175], off
	v_lshl_add_u64 v[174:175], v[178:179], 0, s[24:25]
	s_mov_b32 m0, s72
	s_nop 0
	global_load_lds_dwordx4 v[174:175], off
	v_lshl_add_u64 v[174:175], v[180:181], 0, s[24:25]
	s_mov_b32 m0, s73
	s_nop 0
	global_load_lds_dwordx4 v[174:175], off
	s_waitcnt vmcnt(8)
	s_waitcnt lgkmcnt(0)
	s_setprio 1
	s_barrier
	v_mfma_f32_16x16x32_bf16 v[64:67], v[132:135], v[184:187], v[64:67]
	v_mfma_f32_16x16x32_bf16 v[60:63], v[140:143], v[184:187], v[60:63]
	v_mfma_f32_16x16x32_bf16 v[48:51], v[132:135], v[192:195], v[48:51]
	v_mfma_f32_16x16x32_bf16 v[44:47], v[140:143], v[192:195], v[44:47]
	v_mfma_f32_16x16x32_bf16 v[32:35], v[132:135], v[200:203], v[32:35]
	v_mfma_f32_16x16x32_bf16 v[28:31], v[140:143], v[200:203], v[28:31]
	v_mfma_f32_16x16x32_bf16 v[16:19], v[132:135], v[208:211], v[16:19]
	v_mfma_f32_16x16x32_bf16 v[12:15], v[140:143], v[208:211], v[12:15]
	v_mfma_f32_16x16x32_bf16 v[64:67], v[136:139], v[188:191], v[64:67]
	v_mfma_f32_16x16x32_bf16 v[60:63], v[144:147], v[188:191], v[60:63]
	v_mfma_f32_16x16x32_bf16 v[48:51], v[136:139], v[196:199], v[48:51]
	v_mfma_f32_16x16x32_bf16 v[44:47], v[144:147], v[196:199], v[44:47]
	v_mfma_f32_16x16x32_bf16 v[32:35], v[136:139], v[204:207], v[32:35]
	v_mfma_f32_16x16x32_bf16 v[28:31], v[144:147], v[204:207], v[28:31]
	v_mfma_f32_16x16x32_bf16 v[16:19], v[136:139], v[212:215], v[16:19]
	v_mfma_f32_16x16x32_bf16 v[12:15], v[144:147], v[212:215], v[12:15]
	v_mfma_f32_16x16x32_bf16 v[56:59], v[148:151], v[184:187], v[56:59]
	v_mfma_f32_16x16x32_bf16 v[52:55], v[166:169], v[184:187], v[52:55]
	v_mfma_f32_16x16x32_bf16 v[40:43], v[148:151], v[192:195], v[40:43]
	v_mfma_f32_16x16x32_bf16 v[36:39], v[166:169], v[192:195], v[36:39]
	v_mfma_f32_16x16x32_bf16 v[24:27], v[148:151], v[200:203], v[24:27]
	v_mfma_f32_16x16x32_bf16 v[20:23], v[166:169], v[200:203], v[20:23]
	v_mfma_f32_16x16x32_bf16 v[8:11], v[148:151], v[208:211], v[8:11]
	v_mfma_f32_16x16x32_bf16 v[4:7], v[166:169], v[208:211], v[4:7]
	v_mfma_f32_16x16x32_bf16 v[56:59], v[152:155], v[188:191], v[56:59]
	v_mfma_f32_16x16x32_bf16 v[52:55], v[170:173], v[188:191], v[52:55]
	v_mfma_f32_16x16x32_bf16 v[40:43], v[152:155], v[196:199], v[40:43]
	v_mfma_f32_16x16x32_bf16 v[36:39], v[170:173], v[196:199], v[36:39]
	v_mfma_f32_16x16x32_bf16 v[24:27], v[152:155], v[204:207], v[24:27]
	v_mfma_f32_16x16x32_bf16 v[20:23], v[170:173], v[204:207], v[20:23]
	v_mfma_f32_16x16x32_bf16 v[8:11], v[152:155], v[212:215], v[8:11]
	v_mfma_f32_16x16x32_bf16 v[4:7], v[170:173], v[212:215], v[4:7]
	s_barrier
	s_setprio 0
	s_add_i32 vcc_lo, vcc_lo, 2
	s_add_u32 s44, s44, 0x100
	s_addc_u32 s45, s45, 0
	s_add_u32 s91, s91, 0x100
	s_addc_u32 s96, s96, 0
	s_cmp_gt_u32 vcc_lo, 29
	s_cbranch_scc0 .LBB0_870

.LBB0_1034:
	s_add_u32 vcc_lo, s28, 0x100
	s_addc_u32 vcc_hi, s29, 0
	s_mov_b32 s48, -2
	s_waitcnt lgkmcnt(0)
	s_waitcnt vmcnt(0)
	s_add_u32 s46, s50, 0x100
	s_addc_u32 s47, s51, 0
	s_add_i32 s16, 0, 0x10000
	s_cmpk_eq_i32 s48, 0x54
	s_cselect_b32 s73, s23, s47
	s_cselect_b32 s72, s22, s46
	s_cselect_b32 s29, s27, vcc_hi
	s_cselect_b32 s28, s26, vcc_lo
	s_add_i32 s49, 0, 0x14000
	v_add_u32_e32 v144, s16, v244
	v_add_u32_e32 v160, s49, v244
	ds_read_b128 v[132:135], v144
	ds_read_b128 v[136:139], v144 offset:1024
	ds_read_b128 v[140:143], v144 offset:2048
	ds_read_b128 v[144:147], v144 offset:3072
	ds_read_b128 v[148:151], v160
	ds_read_b128 v[152:155], v160 offset:1024
	ds_read_b128 v[156:159], v160 offset:2048
	ds_read_b128 v[160:163], v160 offset:3072
	v_lshl_add_u64 v[174:175], s[50:51], 0, v[184:185]
	s_add_i32 m0, s77, 0xc000
	ds_read_b128 v[164:167], v246
	ds_read_b128 v[188:191], v246 offset:1024
	ds_read_b128 v[192:195], v246 offset:2048
	ds_read_b128 v[196:199], v246 offset:3072
	ds_read_b128 v[200:203], v246 offset:4096
	ds_read_b128 v[204:207], v246 offset:5120
	ds_read_b128 v[208:211], v246 offset:6144
	ds_read_b128 v[212:215], v246 offset:7168
	global_load_lds_dwordx4 v[174:175], off
	v_lshl_add_u64 v[174:175], s[50:51], 0, v[186:187]
	s_add_i32 m0, s77, 0xe000
	s_nop 0
	global_load_lds_dwordx4 v[174:175], off
	v_mov_b32_e32 v4, 0
	v_mov_b32_e32 v5, v4
	v_mov_b32_e32 v6, v4
	v_mov_b32_e32 v7, v4
	v_mov_b32_e32 v8, v4
	v_mov_b32_e32 v9, v4
	v_mov_b32_e32 v10, v4
	v_mov_b32_e32 v11, v4
	v_mov_b32_e32 v20, v4
	v_mov_b32_e32 v21, v4
	v_mov_b32_e32 v22, v4
	v_mov_b32_e32 v23, v4
	v_mov_b32_e32 v24, v4
	v_mov_b32_e32 v25, v4
	v_mov_b32_e32 v26, v4
	v_mov_b32_e32 v27, v4
	v_mov_b32_e32 v36, v4
	v_mov_b32_e32 v37, v4
	v_mov_b32_e32 v38, v4
	v_mov_b32_e32 v39, v4
	v_mov_b32_e32 v40, v4
	v_mov_b32_e32 v41, v4
	v_mov_b32_e32 v42, v4
	v_mov_b32_e32 v43, v4
	v_mov_b32_e32 v52, v4
	v_mov_b32_e32 v53, v4
	v_mov_b32_e32 v54, v4
	v_mov_b32_e32 v55, v4
	v_mov_b32_e32 v56, v4
	v_mov_b32_e32 v57, v4
	v_mov_b32_e32 v58, v4
	v_mov_b32_e32 v59, v4
	v_mov_b32_e32 v12, v4
	v_mov_b32_e32 v13, v4
	v_mov_b32_e32 v14, v4
	v_mov_b32_e32 v15, v4
	v_mov_b32_e32 v16, v4
	v_mov_b32_e32 v17, v4
	v_mov_b32_e32 v18, v4
	v_mov_b32_e32 v19, v4
	v_mov_b32_e32 v28, v4
	v_mov_b32_e32 v29, v4
	v_mov_b32_e32 v30, v4
	v_mov_b32_e32 v31, v4
	v_mov_b32_e32 v32, v4
	v_mov_b32_e32 v33, v4
	v_mov_b32_e32 v34, v4
	v_mov_b32_e32 v35, v4
	v_mov_b32_e32 v44, v4
	v_mov_b32_e32 v45, v4
	v_mov_b32_e32 v46, v4
	v_mov_b32_e32 v47, v4
	v_mov_b32_e32 v48, v4
	v_mov_b32_e32 v49, v4
	v_mov_b32_e32 v50, v4
	v_mov_b32_e32 v51, v4
	v_mov_b32_e32 v60, v4
	v_mov_b32_e32 v61, v4
	v_mov_b32_e32 v62, v4
	v_mov_b32_e32 v63, v4
	v_mov_b32_e32 v64, v4
	v_mov_b32_e32 v65, v4
	v_mov_b32_e32 v66, v4
	v_mov_b32_e32 v67, v4
	v_mov_b32_e32 v68, v4
	v_mov_b32_e32 v69, v4
	v_mov_b32_e32 v70, v4
	v_mov_b32_e32 v71, v4
	v_mov_b32_e32 v72, v4
	v_mov_b32_e32 v73, v4
	v_mov_b32_e32 v74, v4
	v_mov_b32_e32 v75, v4
	v_mov_b32_e32 v84, v4
	v_mov_b32_e32 v85, v4
	v_mov_b32_e32 v86, v4
	v_mov_b32_e32 v87, v4
	v_mov_b32_e32 v88, v4
	v_mov_b32_e32 v89, v4
	v_mov_b32_e32 v90, v4
	v_mov_b32_e32 v91, v4
	v_mov_b32_e32 v100, v4
	v_mov_b32_e32 v101, v4
	v_mov_b32_e32 v102, v4
	v_mov_b32_e32 v103, v4
	v_mov_b32_e32 v104, v4
	v_mov_b32_e32 v105, v4
	v_mov_b32_e32 v106, v4
	v_mov_b32_e32 v107, v4
	v_mov_b32_e32 v116, v4
	v_mov_b32_e32 v117, v4
	v_mov_b32_e32 v118, v4
	v_mov_b32_e32 v119, v4
	v_mov_b32_e32 v120, v4
	v_mov_b32_e32 v121, v4
	v_mov_b32_e32 v122, v4
	v_mov_b32_e32 v123, v4
	v_mov_b32_e32 v76, v4
	v_mov_b32_e32 v77, v4
	v_mov_b32_e32 v78, v4
	v_mov_b32_e32 v79, v4
	v_mov_b32_e32 v80, v4
	v_mov_b32_e32 v81, v4
	v_mov_b32_e32 v82, v4
	v_mov_b32_e32 v83, v4
	v_mov_b32_e32 v92, v4
	v_mov_b32_e32 v93, v4
	v_mov_b32_e32 v94, v4
	v_mov_b32_e32 v95, v4
	v_mov_b32_e32 v96, v4
	v_mov_b32_e32 v97, v4
	v_mov_b32_e32 v98, v4
	v_mov_b32_e32 v99, v4
	v_mov_b32_e32 v108, v4
	v_mov_b32_e32 v109, v4
	v_mov_b32_e32 v110, v4
	v_mov_b32_e32 v111, v4
	v_mov_b32_e32 v112, v4
	v_mov_b32_e32 v113, v4
	v_mov_b32_e32 v114, v4
	v_mov_b32_e32 v115, v4
	v_mov_b32_e32 v124, v4
	v_mov_b32_e32 v125, v4
	v_mov_b32_e32 v126, v4
	v_mov_b32_e32 v127, v4
	v_mov_b32_e32 v128, v4
	v_mov_b32_e32 v129, v4
	v_mov_b32_e32 v130, v4
	v_mov_b32_e32 v131, v4
	s_branch .Lmid_1035

.Lmid_1035:
	s_waitcnt vmcnt(8)
	s_waitcnt lgkmcnt(0)
	s_setprio 1
	s_barrier
	v_mfma_f32_16x16x32_bf16 v[128:131], v[132:135], v[164:167], v[128:131]
	v_mfma_f32_16x16x32_bf16 v[124:127], v[140:143], v[164:167], v[124:127]
	v_mfma_f32_16x16x32_bf16 v[112:115], v[132:135], v[192:195], v[112:115]
	v_mfma_f32_16x16x32_bf16 v[108:111], v[140:143], v[192:195], v[108:111]
	v_mfma_f32_16x16x32_bf16 v[96:99], v[132:135], v[200:203], v[96:99]
	v_mfma_f32_16x16x32_bf16 v[92:95], v[140:143], v[200:203], v[92:95]
	v_mfma_f32_16x16x32_bf16 v[80:83], v[132:135], v[208:211], v[80:83]
	v_mfma_f32_16x16x32_bf16 v[76:79], v[140:143], v[208:211], v[76:79]
	v_mfma_f32_16x16x32_bf16 v[128:131], v[136:139], v[188:191], v[128:131]
	v_mfma_f32_16x16x32_bf16 v[124:127], v[144:147], v[188:191], v[124:127]
	v_mfma_f32_16x16x32_bf16 v[112:115], v[136:139], v[196:199], v[112:115]
	v_mfma_f32_16x16x32_bf16 v[108:111], v[144:147], v[196:199], v[108:111]
	v_mfma_f32_16x16x32_bf16 v[96:99], v[136:139], v[204:207], v[96:99]
	v_mfma_f32_16x16x32_bf16 v[92:95], v[144:147], v[204:207], v[92:95]
	v_mfma_f32_16x16x32_bf16 v[80:83], v[136:139], v[212:215], v[80:83]
	v_mfma_f32_16x16x32_bf16 v[76:79], v[144:147], v[212:215], v[76:79]
	v_mfma_f32_16x16x32_bf16 v[120:123], v[148:151], v[164:167], v[120:123]
	v_mfma_f32_16x16x32_bf16 v[116:119], v[156:159], v[164:167], v[116:119]
	v_mfma_f32_16x16x32_bf16 v[104:107], v[148:151], v[192:195], v[104:107]
	v_mfma_f32_16x16x32_bf16 v[100:103], v[156:159], v[192:195], v[100:103]
	v_mfma_f32_16x16x32_bf16 v[88:91], v[148:151], v[200:203], v[88:91]
	v_mfma_f32_16x16x32_bf16 v[84:87], v[156:159], v[200:203], v[84:87]
	v_mfma_f32_16x16x32_bf16 v[72:75], v[148:151], v[208:211], v[72:75]
	v_mfma_f32_16x16x32_bf16 v[68:71], v[156:159], v[208:211], v[68:71]
	v_mfma_f32_16x16x32_bf16 v[120:123], v[152:155], v[188:191], v[120:123]
	v_mfma_f32_16x16x32_bf16 v[116:119], v[160:163], v[188:191], v[116:119]
	v_mfma_f32_16x16x32_bf16 v[104:107], v[152:155], v[196:199], v[104:107]
	v_mfma_f32_16x16x32_bf16 v[100:103], v[160:163], v[196:199], v[100:103]
	v_mfma_f32_16x16x32_bf16 v[88:91], v[152:155], v[204:207], v[88:91]
	v_mfma_f32_16x16x32_bf16 v[84:87], v[160:163], v[204:207], v[84:87]
	v_mfma_f32_16x16x32_bf16 v[72:75], v[152:155], v[212:215], v[72:75]
	v_mfma_f32_16x16x32_bf16 v[68:71], v[160:163], v[212:215], v[68:71]
	s_barrier
	s_setprio 0
	s_add_i32 s16, s16, s74
	v_lshl_add_u64 v[174:175], s[28:29], 0, v[2:3]
	s_mov_b32 m0, s16
	ds_read_b128 v[164:167], v246 offset:16384
	ds_read_b128 v[188:191], v246 offset:17408
	ds_read_b128 v[192:195], v246 offset:18432
	ds_read_b128 v[196:199], v246 offset:19456
	ds_read_b128 v[200:203], v246 offset:20480
	ds_read_b128 v[204:207], v246 offset:21504
	ds_read_b128 v[208:211], v246 offset:22528
	ds_read_b128 v[212:215], v246 offset:23552
	global_load_lds_dwordx4 v[174:175], off
	s_add_i32 m0, s16, 0x2000
	s_add_u32 s16, s28, 0x58000
	v_lshl_add_u64 v[176:177], s[28:29], 0, v[168:169]
	s_addc_u32 s17, s29, 0
	s_add_i32 s49, s49, s74
	global_load_lds_dwordx4 v[176:177], off
	v_lshl_add_u64 v[178:179], s[16:17], 0, v[2:3]
	s_mov_b32 m0, s49
	v_lshl_add_u64 v[180:181], s[72:73], 0, v[170:171]
	global_load_lds_dwordx4 v[178:179], off
	v_lshl_add_u64 v[178:179], s[16:17], 0, v[168:169]
	s_add_i32 m0, s49, 0x2000
	s_nop 0
	global_load_lds_dwordx4 v[178:179], off
	v_lshl_add_u64 v[178:179], s[72:73], 0, v[172:173]
	s_mov_b32 m0, s77
	s_nop 0
	global_load_lds_dwordx4 v[178:179], off
	s_mov_b32 m0, s78
	s_nop 0
	global_load_lds_dwordx4 v[180:181], off
	s_waitcnt vmcnt(8)
	s_waitcnt lgkmcnt(0)
	s_setprio 1
	s_barrier
	v_mfma_f32_16x16x32_bf16 v[64:67], v[132:135], v[164:167], v[64:67]
	v_mfma_f32_16x16x32_bf16 v[60:63], v[140:143], v[164:167], v[60:63]
	v_mfma_f32_16x16x32_bf16 v[48:51], v[132:135], v[192:195], v[48:51]
	v_mfma_f32_16x16x32_bf16 v[44:47], v[140:143], v[192:195], v[44:47]
	v_mfma_f32_16x16x32_bf16 v[32:35], v[132:135], v[200:203], v[32:35]
	v_mfma_f32_16x16x32_bf16 v[28:31], v[140:143], v[200:203], v[28:31]
	v_mfma_f32_16x16x32_bf16 v[16:19], v[132:135], v[208:211], v[16:19]
	v_mfma_f32_16x16x32_bf16 v[12:15], v[140:143], v[208:211], v[12:15]
	v_mfma_f32_16x16x32_bf16 v[64:67], v[136:139], v[188:191], v[64:67]
	v_mfma_f32_16x16x32_bf16 v[60:63], v[144:147], v[188:191], v[60:63]
	v_mfma_f32_16x16x32_bf16 v[48:51], v[136:139], v[196:199], v[48:51]
	v_mfma_f32_16x16x32_bf16 v[44:47], v[144:147], v[196:199], v[44:47]
	v_mfma_f32_16x16x32_bf16 v[32:35], v[136:139], v[204:207], v[32:35]
	v_mfma_f32_16x16x32_bf16 v[28:31], v[144:147], v[204:207], v[28:31]
	v_mfma_f32_16x16x32_bf16 v[16:19], v[136:139], v[212:215], v[16:19]
	v_mfma_f32_16x16x32_bf16 v[12:15], v[144:147], v[212:215], v[12:15]
	v_mfma_f32_16x16x32_bf16 v[56:59], v[148:151], v[164:167], v[56:59]
	v_mfma_f32_16x16x32_bf16 v[52:55], v[156:159], v[164:167], v[52:55]
	v_mfma_f32_16x16x32_bf16 v[40:43], v[148:151], v[192:195], v[40:43]
	v_mfma_f32_16x16x32_bf16 v[36:39], v[156:159], v[192:195], v[36:39]
	v_mfma_f32_16x16x32_bf16 v[24:27], v[148:151], v[200:203], v[24:27]
	v_mfma_f32_16x16x32_bf16 v[20:23], v[156:159], v[200:203], v[20:23]
	v_mfma_f32_16x16x32_bf16 v[8:11], v[148:151], v[208:211], v[8:11]
	v_mfma_f32_16x16x32_bf16 v[4:7], v[156:159], v[208:211], v[4:7]
	v_mfma_f32_16x16x32_bf16 v[56:59], v[152:155], v[188:191], v[56:59]
	v_mfma_f32_16x16x32_bf16 v[52:55], v[160:163], v[188:191], v[52:55]
	v_mfma_f32_16x16x32_bf16 v[40:43], v[152:155], v[196:199], v[40:43]
	v_mfma_f32_16x16x32_bf16 v[36:39], v[160:163], v[196:199], v[36:39]
	v_mfma_f32_16x16x32_bf16 v[24:27], v[152:155], v[204:207], v[24:27]
	v_mfma_f32_16x16x32_bf16 v[20:23], v[160:163], v[204:207], v[20:23]
	v_mfma_f32_16x16x32_bf16 v[8:11], v[152:155], v[212:215], v[8:11]
	v_mfma_f32_16x16x32_bf16 v[4:7], v[160:163], v[212:215], v[4:7]
	s_barrier
	s_setprio 0
	s_add_i32 s49, 0, 0x18000
	s_add_i32 s50, 0, 0x1c000
	v_add_u32_e32 v144, s49, v244
	v_add_u32_e32 v160, s50, v244
	ds_read_b128 v[132:135], v144
	ds_read_b128 v[136:139], v144 offset:1024
	ds_read_b128 v[140:143], v144 offset:2048
	ds_read_b128 v[144:147], v144 offset:3072
	ds_read_b128 v[148:151], v160
	ds_read_b128 v[152:155], v160 offset:1024
	ds_read_b128 v[156:159], v160 offset:2048
	ds_read_b128 v[160:163], v160 offset:3072
	s_add_u32 s16, s72, 0x160000
	s_addc_u32 s17, s73, 0
	s_mov_b32 m0, s18
	v_lshl_add_u64 v[182:183], s[16:17], 0, v[172:173]
	ds_read_b128 v[164:167], v246 offset:32768
	ds_read_b128 v[188:191], v246 offset:33792
	ds_read_b128 v[192:195], v246 offset:34816
	ds_read_b128 v[196:199], v246 offset:35840
	ds_read_b128 v[200:203], v246 offset:36864
	ds_read_b128 v[204:207], v246 offset:37888
	ds_read_b128 v[208:211], v246 offset:38912
	ds_read_b128 v[212:215], v246 offset:39936
	global_load_lds_dwordx4 v[182:183], off
	v_lshl_add_u64 v[182:183], s[16:17], 0, v[170:171]
	s_mov_b32 m0, s19
	s_nop 0
	global_load_lds_dwordx4 v[182:183], off
	s_waitcnt vmcnt(8)
	s_waitcnt lgkmcnt(0)
	s_setprio 1
	s_barrier
	v_mfma_f32_16x16x32_bf16 v[128:131], v[132:135], v[164:167], v[128:131]
	v_mfma_f32_16x16x32_bf16 v[124:127], v[140:143], v[164:167], v[124:127]
	v_mfma_f32_16x16x32_bf16 v[112:115], v[132:135], v[192:195], v[112:115]
	v_mfma_f32_16x16x32_bf16 v[108:111], v[140:143], v[192:195], v[108:111]
	v_mfma_f32_16x16x32_bf16 v[96:99], v[132:135], v[200:203], v[96:99]
	v_mfma_f32_16x16x32_bf16 v[92:95], v[140:143], v[200:203], v[92:95]
	v_mfma_f32_16x16x32_bf16 v[80:83], v[132:135], v[208:211], v[80:83]
	v_mfma_f32_16x16x32_bf16 v[76:79], v[140:143], v[208:211], v[76:79]
	v_mfma_f32_16x16x32_bf16 v[128:131], v[136:139], v[188:191], v[128:131]
	v_mfma_f32_16x16x32_bf16 v[124:127], v[144:147], v[188:191], v[124:127]
	v_mfma_f32_16x16x32_bf16 v[112:115], v[136:139], v[196:199], v[112:115]
	v_mfma_f32_16x16x32_bf16 v[108:111], v[144:147], v[196:199], v[108:111]
	v_mfma_f32_16x16x32_bf16 v[96:99], v[136:139], v[204:207], v[96:99]
	v_mfma_f32_16x16x32_bf16 v[92:95], v[144:147], v[204:207], v[92:95]
	v_mfma_f32_16x16x32_bf16 v[80:83], v[136:139], v[212:215], v[80:83]
	v_mfma_f32_16x16x32_bf16 v[76:79], v[144:147], v[212:215], v[76:79]
	v_mfma_f32_16x16x32_bf16 v[120:123], v[148:151], v[164:167], v[120:123]
	v_mfma_f32_16x16x32_bf16 v[116:119], v[156:159], v[164:167], v[116:119]
	v_mfma_f32_16x16x32_bf16 v[104:107], v[148:151], v[192:195], v[104:107]
	v_mfma_f32_16x16x32_bf16 v[100:103], v[156:159], v[192:195], v[100:103]
	v_mfma_f32_16x16x32_bf16 v[88:91], v[148:151], v[200:203], v[88:91]
	v_mfma_f32_16x16x32_bf16 v[84:87], v[156:159], v[200:203], v[84:87]
	v_mfma_f32_16x16x32_bf16 v[72:75], v[148:151], v[208:211], v[72:75]
	v_mfma_f32_16x16x32_bf16 v[68:71], v[156:159], v[208:211], v[68:71]
	v_mfma_f32_16x16x32_bf16 v[120:123], v[152:155], v[188:191], v[120:123]
	v_mfma_f32_16x16x32_bf16 v[116:119], v[160:163], v[188:191], v[116:119]
	v_mfma_f32_16x16x32_bf16 v[104:107], v[152:155], v[196:199], v[104:107]
	v_mfma_f32_16x16x32_bf16 v[100:103], v[160:163], v[196:199], v[100:103]
	v_mfma_f32_16x16x32_bf16 v[88:91], v[152:155], v[204:207], v[88:91]
	v_mfma_f32_16x16x32_bf16 v[84:87], v[160:163], v[204:207], v[84:87]
	v_mfma_f32_16x16x32_bf16 v[72:75], v[152:155], v[212:215], v[72:75]
	v_mfma_f32_16x16x32_bf16 v[68:71], v[160:163], v[212:215], v[68:71]
	s_barrier
	s_setprio 0
	s_add_i32 s16, s49, s74
	v_lshl_add_u64 v[174:175], v[174:175], 0, s[24:25]
	s_mov_b32 m0, s16
	ds_read_b128 v[164:167], v246 offset:49152
	ds_read_b128 v[188:191], v246 offset:50176
	ds_read_b128 v[192:195], v246 offset:51200
	ds_read_b128 v[196:199], v246 offset:52224
	ds_read_b128 v[200:203], v246 offset:53248
	ds_read_b128 v[204:207], v246 offset:54272
	ds_read_b128 v[208:211], v246 offset:55296
	ds_read_b128 v[212:215], v246 offset:56320
	global_load_lds_dwordx4 v[174:175], off
	s_add_i32 m0, s16, 0x2000
	s_add_u32 s16, s28, 0x58080
	v_lshl_add_u64 v[174:175], v[176:177], 0, s[24:25]
	s_addc_u32 s17, s29, 0
	s_add_i32 s28, s50, s74
	global_load_lds_dwordx4 v[174:175], off
	v_lshl_add_u64 v[174:175], s[16:17], 0, v[2:3]
	s_mov_b32 m0, s28
	s_nop 0
	global_load_lds_dwordx4 v[174:175], off
	v_lshl_add_u64 v[174:175], s[16:17], 0, v[168:169]
	s_add_i32 m0, s28, 0x2000
	s_nop 0
	global_load_lds_dwordx4 v[174:175], off
	v_lshl_add_u64 v[174:175], v[178:179], 0, s[24:25]
	s_mov_b32 m0, s96
	s_nop 0
	global_load_lds_dwordx4 v[174:175], off
	v_lshl_add_u64 v[174:175], v[180:181], 0, s[24:25]
	s_mov_b32 m0, s3
	s_nop 0
	global_load_lds_dwordx4 v[174:175], off
	s_waitcnt vmcnt(8)
	s_waitcnt lgkmcnt(0)
	s_setprio 1
	s_barrier
	v_mfma_f32_16x16x32_bf16 v[64:67], v[132:135], v[164:167], v[64:67]
	v_mfma_f32_16x16x32_bf16 v[60:63], v[140:143], v[164:167], v[60:63]
	v_mfma_f32_16x16x32_bf16 v[48:51], v[132:135], v[192:195], v[48:51]
	v_mfma_f32_16x16x32_bf16 v[44:47], v[140:143], v[192:195], v[44:47]
	v_mfma_f32_16x16x32_bf16 v[32:35], v[132:135], v[200:203], v[32:35]
	v_mfma_f32_16x16x32_bf16 v[28:31], v[140:143], v[200:203], v[28:31]
	v_mfma_f32_16x16x32_bf16 v[16:19], v[132:135], v[208:211], v[16:19]
	v_mfma_f32_16x16x32_bf16 v[12:15], v[140:143], v[208:211], v[12:15]
	v_mfma_f32_16x16x32_bf16 v[64:67], v[136:139], v[188:191], v[64:67]
	v_mfma_f32_16x16x32_bf16 v[60:63], v[144:147], v[188:191], v[60:63]
	v_mfma_f32_16x16x32_bf16 v[48:51], v[136:139], v[196:199], v[48:51]
	v_mfma_f32_16x16x32_bf16 v[44:47], v[144:147], v[196:199], v[44:47]
	v_mfma_f32_16x16x32_bf16 v[32:35], v[136:139], v[204:207], v[32:35]
	v_mfma_f32_16x16x32_bf16 v[28:31], v[144:147], v[204:207], v[28:31]
	v_mfma_f32_16x16x32_bf16 v[16:19], v[136:139], v[212:215], v[16:19]
	v_mfma_f32_16x16x32_bf16 v[12:15], v[144:147], v[212:215], v[12:15]
	v_mfma_f32_16x16x32_bf16 v[56:59], v[148:151], v[164:167], v[56:59]
	v_mfma_f32_16x16x32_bf16 v[52:55], v[156:159], v[164:167], v[52:55]
	v_mfma_f32_16x16x32_bf16 v[40:43], v[148:151], v[192:195], v[40:43]
	v_mfma_f32_16x16x32_bf16 v[36:39], v[156:159], v[192:195], v[36:39]
	v_mfma_f32_16x16x32_bf16 v[24:27], v[148:151], v[200:203], v[24:27]
	v_mfma_f32_16x16x32_bf16 v[20:23], v[156:159], v[200:203], v[20:23]
	v_mfma_f32_16x16x32_bf16 v[8:11], v[148:151], v[208:211], v[8:11]
	v_mfma_f32_16x16x32_bf16 v[4:7], v[156:159], v[208:211], v[4:7]
	v_mfma_f32_16x16x32_bf16 v[56:59], v[152:155], v[188:191], v[56:59]
	v_mfma_f32_16x16x32_bf16 v[52:55], v[160:163], v[188:191], v[52:55]
	v_mfma_f32_16x16x32_bf16 v[40:43], v[152:155], v[196:199], v[40:43]
	v_mfma_f32_16x16x32_bf16 v[36:39], v[160:163], v[196:199], v[36:39]
	v_mfma_f32_16x16x32_bf16 v[24:27], v[152:155], v[204:207], v[24:27]
	v_mfma_f32_16x16x32_bf16 v[20:23], v[160:163], v[204:207], v[20:23]
	v_mfma_f32_16x16x32_bf16 v[8:11], v[152:155], v[212:215], v[8:11]
	v_mfma_f32_16x16x32_bf16 v[4:7], v[160:163], v[212:215], v[4:7]
	s_barrier
	s_setprio 0
	s_add_i32 s48, s48, 2
	s_add_u32 vcc_lo, vcc_lo, 0x100
	s_addc_u32 vcc_hi, vcc_hi, 0
	s_cmpk_gt_u32 s48, 0x55
	s_mov_b64 s[50:51], s[46:47]
	s_cbranch_scc0 .LBB0_1035
	v_readlane_b32 s16, v252, 12
	v_readlane_b32 s17, v252, 13
